# split packed fp32 VALU (v_pk_fma/mul/add_f32) into scalar pairs in the three attention phases (bit-identical; packed fp32 beside MFMAs is an anti-lever)
# speedup vs baseline: 1.4108x; 1.0009x over previous
.LBB0_670:
	ds_bpermute_b32 v0, v209, v193
	v_lshlrev_b64 v[2:3], 11, v[194:195]
	s_mov_b32 s19, s7
	v_lshl_add_u64 v[2:3], s[4:5], 0, v[2:3]
	v_lshl_add_u64 v[2:3], s[18:19], 1, v[2:3]
	s_waitcnt lgkmcnt(0)
	v_add_f32_e32 v0, v193, v0
	v_div_scale_f32 v4, s[20:21], v0, v0, 1.0
	v_rcp_f32_e32 v5, v4
	v_div_scale_f32 v6, vcc, 1.0, v0, 1.0
	v_mov_b32_e32 v193, v1
	v_fma_f32 v7, -v4, v5, 1.0
	v_fmac_f32_e32 v5, v7, v5
	v_mul_f32_e32 v7, v6, v5
	v_fma_f32 v8, -v4, v7, v6
	v_fmac_f32_e32 v7, v8, v5
	v_fma_f32 v4, -v4, v7, v6
	v_div_fmas_f32 v4, v4, v5, v7
	v_div_fixup_f32 v0, v4, v0, 1.0
	v_mul_f32_e32 v4, v64, v0
	v_mul_f32_e32 v5, v65, v0
	v_mul_f32_e32 v6, v66, v0
	v_mul_f32_e32 v7, v67, v0
	v_mul_f32_e32 v8, v68, v0
	v_mul_f32_e32 v9, v69, v0
	v_mul_f32_e32 v10, v70, v0
	v_mul_f32_e32 v11, v71, v0
	v_lshl_add_u64 v[2:3], v[2:3], 0, v[192:193]
	v_cvt_pk_bf16_f32 v4, v4, v5
	v_cvt_pk_bf16_f32 v5, v6, v7
	v_mul_f32_e32 v12, v72, v0
	v_mul_f32_e32 v13, v73, v0
	v_mul_f32_e32 v14, v74, v0
	v_mul_f32_e32 v15, v75, v0
	global_store_dwordx2 v[2:3], v[4:5], off sc1
	v_cvt_pk_bf16_f32 v4, v8, v9
	v_cvt_pk_bf16_f32 v5, v10, v11
	v_mul_f32_e32 v64, v76, v0
	v_mul_f32_e32 v65, v77, v0
	v_mul_f32_e32 v66, v78, v0
	v_mul_f32_e32 v67, v79, v0
	global_store_dwordx2 v[2:3], v[4:5], off offset:16 sc1
	v_cvt_pk_bf16_f32 v4, v12, v13
	v_cvt_pk_bf16_f32 v5, v14, v15
	v_mul_f32_e32 v48, v48, v0
	v_mul_f32_e32 v49, v49, v0
	v_mul_f32_e32 v50, v50, v0
	v_mul_f32_e32 v51, v51, v0
	global_store_dwordx2 v[2:3], v[4:5], off offset:32 sc1
	v_cvt_pk_bf16_f32 v4, v64, v65
	v_cvt_pk_bf16_f32 v5, v66, v67
	v_mul_f32_e32 v52, v52, v0
	v_mul_f32_e32 v53, v53, v0
	v_mul_f32_e32 v54, v54, v0
	v_mul_f32_e32 v55, v55, v0
	global_store_dwordx2 v[2:3], v[4:5], off offset:48 sc1
	v_cvt_pk_bf16_f32 v4, v48, v49
	v_cvt_pk_bf16_f32 v5, v50, v51
	v_mul_f32_e32 v56, v56, v0
	v_mul_f32_e32 v57, v57, v0
	v_mul_f32_e32 v58, v58, v0
	v_mul_f32_e32 v59, v59, v0
	global_store_dwordx2 v[2:3], v[4:5], off offset:64 sc1
	v_cvt_pk_bf16_f32 v4, v52, v53
	v_cvt_pk_bf16_f32 v5, v54, v55
	v_mul_f32_e32 v60, v60, v0
	v_mul_f32_e32 v61, v61, v0
	v_mul_f32_e32 v62, v62, v0
	v_mul_f32_e32 v63, v63, v0
	global_store_dwordx2 v[2:3], v[4:5], off offset:80 sc1
	v_cvt_pk_bf16_f32 v4, v56, v57
	v_cvt_pk_bf16_f32 v5, v58, v59
	v_mul_f32_e32 v32, v32, v0
	v_mul_f32_e32 v33, v33, v0
	v_mul_f32_e32 v34, v34, v0
	v_mul_f32_e32 v35, v35, v0
	global_store_dwordx2 v[2:3], v[4:5], off offset:96 sc1
	v_cvt_pk_bf16_f32 v4, v60, v61
	v_cvt_pk_bf16_f32 v5, v62, v63
	v_mul_f32_e32 v36, v36, v0
	v_mul_f32_e32 v37, v37, v0
	v_mul_f32_e32 v38, v38, v0
	v_mul_f32_e32 v39, v39, v0
	global_store_dwordx2 v[2:3], v[4:5], off offset:112 sc1
	v_cvt_pk_bf16_f32 v4, v32, v33
	v_cvt_pk_bf16_f32 v5, v34, v35
	v_mul_f32_e32 v40, v40, v0
	v_mul_f32_e32 v41, v41, v0
	v_mul_f32_e32 v42, v42, v0
	v_mul_f32_e32 v43, v43, v0
	global_store_dwordx2 v[2:3], v[4:5], off offset:128 sc1
	v_cvt_pk_bf16_f32 v4, v36, v37
	v_cvt_pk_bf16_f32 v5, v38, v39
	v_mul_f32_e32 v44, v44, v0
	v_mul_f32_e32 v45, v45, v0
	v_mul_f32_e32 v46, v46, v0
	v_mul_f32_e32 v47, v47, v0
	global_store_dwordx2 v[2:3], v[4:5], off offset:144 sc1
	v_cvt_pk_bf16_f32 v4, v40, v41
	v_cvt_pk_bf16_f32 v5, v42, v43
	v_mul_f32_e32 v16, v16, v0
	v_mul_f32_e32 v17, v17, v0
	v_mul_f32_e32 v18, v18, v0
	v_mul_f32_e32 v19, v19, v0
	global_store_dwordx2 v[2:3], v[4:5], off offset:160 sc1
	v_cvt_pk_bf16_f32 v4, v44, v45
	v_cvt_pk_bf16_f32 v5, v46, v47
	v_mul_f32_e32 v20, v20, v0
	v_mul_f32_e32 v21, v21, v0
	v_mul_f32_e32 v22, v22, v0
	v_mul_f32_e32 v23, v23, v0
	global_store_dwordx2 v[2:3], v[4:5], off offset:176 sc1
	v_cvt_pk_bf16_f32 v4, v16, v17
	v_cvt_pk_bf16_f32 v5, v18, v19
	v_mul_f32_e32 v24, v24, v0
	v_mul_f32_e32 v25, v25, v0
	v_mul_f32_e32 v26, v26, v0
	v_mul_f32_e32 v27, v27, v0
	global_store_dwordx2 v[2:3], v[4:5], off offset:192 sc1
	v_cvt_pk_bf16_f32 v4, v20, v21
	v_cvt_pk_bf16_f32 v5, v22, v23
	v_mul_f32_e32 v28, v28, v0
	v_mul_f32_e32 v29, v29, v0
	v_mul_f32_e32 v30, v30, v0
	v_mul_f32_e32 v31, v31, v0
	global_store_dwordx2 v[2:3], v[4:5], off offset:208 sc1
	v_cvt_pk_bf16_f32 v4, v24, v25
	v_cvt_pk_bf16_f32 v5, v26, v27
	s_add_i32 s37, s37, s33
	global_store_dwordx2 v[2:3], v[4:5], off offset:224 sc1
	v_cvt_pk_bf16_f32 v4, v28, v29
	v_cvt_pk_bf16_f32 v5, v30, v31
	s_cmpk_gt_i32 s37, 0x3ff
	global_store_dwordx2 v[2:3], v[4:5], off offset:240 sc1
	s_cbranch_scc1 .LBB0_687

.LBB0_684:
	v_fma_f32 v2, v80, s8, -v198
	v_fma_f32 v3, v81, s8, -v198
	v_lshl_add_u32 v0, s38, 6, v211
	v_exp_f32_e32 v14, v2
	v_exp_f32_e32 v15, v3
	v_fma_f32 v2, v82, s8, -v198
	v_fma_f32 v3, v83, s8, -v198
	v_fma_f32 v6, v86, s8, -v198
	v_fma_f32 v7, v87, s8, -v198
	v_exp_f32_e32 v216, v2
	v_exp_f32_e32 v217, v3
	v_fma_f32 v2, v84, s8, -v198
	v_fma_f32 v3, v85, s8, -v198
	v_exp_f32_e32 v220, v6
	v_exp_f32_e32 v218, v2
	v_exp_f32_e32 v219, v3
	ds_read_b128 v[2:5], v0 offset:25600
	ds_read_b128 v[10:13], v0 offset:25632
	v_exp_f32_e32 v221, v7
	v_cvt_pk_bf16_f32 v6, v14, v15
	v_cvt_pk_bf16_f32 v7, v216, v217
	v_cvt_pk_bf16_f32 v8, v218, v219
	v_cvt_pk_bf16_f32 v9, v220, v221
	v_fma_f32 v84, v88, s8, -v198
	v_fma_f32 v85, v89, s8, -v198
	s_xor_b64 s[40:41], s[28:29], -1
	s_waitcnt lgkmcnt(1)
	v_mfma_f32_32x32x16_bf16 v[64:79], v[2:5], v[6:9], v[64:79]
	ds_read_b128 v[2:5], v0 offset:30208
	ds_read_b128 v[80:83], v0 offset:30240
	v_exp_f32_e32 v88, v84
	v_exp_f32_e32 v89, v85
	s_mov_b32 s38, 1
	s_mov_b64 s[28:29], 0
	s_and_b64 vcc, exec, s[40:41]
	s_waitcnt lgkmcnt(1)
	v_mfma_f32_32x32x16_bf16 v[48:63], v[2:5], v[6:9], v[48:63]
	ds_read_b128 v[2:5], v0 offset:34816
	ds_read_b128 v[84:87], v0 offset:39424
	ds_read_b128 v[212:215], v0 offset:34848
	s_waitcnt lgkmcnt(2)
	v_mfma_f32_32x32x16_bf16 v[32:47], v[2:5], v[6:9], v[32:47]
	v_fma_f32 v2, v90, s8, -v198
	v_fma_f32 v3, v91, s8, -v198
	v_exp_f32_e32 v90, v2
	v_exp_f32_e32 v91, v3
	v_fma_f32 v2, v92, s8, -v198
	v_fma_f32 v3, v93, s8, -v198
	s_nop 0
	v_exp_f32_e32 v92, v2
	v_exp_f32_e32 v93, v3
	ds_read_b128 v[2:5], v0 offset:39456
	s_waitcnt lgkmcnt(2)
	v_mfma_f32_32x32x16_bf16 v[16:31], v[84:87], v[6:9], v[16:31]
	v_fma_f32 v6, v94, s8, -v198
	v_fma_f32 v7, v95, s8, -v198
	v_cvt_pk_bf16_f32 v8, v92, v93
	v_exp_f32_e32 v84, v6
	v_exp_f32_e32 v85, v7
	v_cvt_pk_bf16_f32 v6, v88, v89
	v_cvt_pk_bf16_f32 v7, v90, v91
	v_cvt_pk_bf16_f32 v9, v84, v85
	s_nop 1
	v_mfma_f32_32x32x16_bf16 v[64:79], v[10:13], v[6:9], v[64:79]
	v_add_f32_e64 v10, v14, 0
	v_add_f32_e64 v11, v15, 0
	v_add_f32_e64 v10, v216, v10
	v_add_f32_e64 v11, v217, v11
	v_add_f32_e64 v10, v218, v10
	v_add_f32_e64 v11, v219, v11
	v_add_f32_e32 v10, v220, v10
	v_add_f32_e32 v11, v221, v11
	v_mfma_f32_32x32x16_bf16 v[48:63], v[80:83], v[6:9], v[48:63]
	v_add_f32_e64 v10, v88, v10
	v_add_f32_e64 v11, v89, v11
	v_add_f32_e64 v10, v90, v10
	v_add_f32_e64 v11, v91, v11
	v_add_f32_e64 v10, v92, v10
	v_add_f32_e64 v11, v93, v11
	v_add_f32_e32 v10, v84, v10
	v_add_f32_e32 v11, v85, v11
	s_waitcnt lgkmcnt(1)
	v_mfma_f32_32x32x16_bf16 v[32:47], v[212:215], v[6:9], v[32:47]
	v_add_f32_e32 v0, v10, v11
	v_add_f32_e32 v193, v193, v0
	s_waitcnt lgkmcnt(0)
	v_mfma_f32_32x32x16_bf16 v[16:31], v[2:5], v[6:9], v[16:31]
	s_cbranch_vccnz .LBB0_680
.LBB0_685:
	v_lshl_or_b32 v0, s38, 5, v202
	v_mad_u32_u24 v0, v0, s30, v208
	ds_read_b128 v[2:5], v0
	ds_read_b128 v[6:9], v0 offset:32
	s_waitcnt lgkmcnt(1)
	v_mfma_f32_32x32x16_bf16 v[80:95], v[2:5], v[148:151], 0
	s_waitcnt lgkmcnt(0)
	v_mfma_f32_32x32x16_bf16 v[80:95], v[6:9], v[96:99], v[80:95]
	ds_read_b128 v[2:5], v0 offset:64
	ds_read_b128 v[6:9], v0 offset:96
	s_waitcnt lgkmcnt(1)
	v_mfma_f32_32x32x16_bf16 v[80:95], v[2:5], v[100:103], v[80:95]
	s_waitcnt lgkmcnt(0)
	v_mfma_f32_32x32x16_bf16 v[80:95], v[6:9], v[104:107], v[80:95]
	ds_read_b128 v[2:5], v0 offset:128
	ds_read_b128 v[6:9], v0 offset:160
	s_waitcnt lgkmcnt(1)
	v_mfma_f32_32x32x16_bf16 v[80:95], v[2:5], v[108:111], v[80:95]
	s_waitcnt lgkmcnt(0)
	v_mfma_f32_32x32x16_bf16 v[80:95], v[6:9], v[112:115], v[80:95]
	ds_read_b128 v[2:5], v0 offset:192
	ds_read_b128 v[6:9], v0 offset:224
	s_waitcnt lgkmcnt(1)
	v_mfma_f32_32x32x16_bf16 v[80:95], v[2:5], v[116:119], v[80:95]
	s_waitcnt lgkmcnt(0)
	v_mfma_f32_32x32x16_bf16 v[80:95], v[6:9], v[120:123], v[80:95]
	ds_read_b128 v[2:5], v0 offset:256
	ds_read_b128 v[6:9], v0 offset:288
	s_waitcnt lgkmcnt(1)
	v_mfma_f32_32x32x16_bf16 v[80:95], v[2:5], v[124:127], v[80:95]
	s_waitcnt lgkmcnt(0)
	v_mfma_f32_32x32x16_bf16 v[80:95], v[6:9], v[128:131], v[80:95]
	ds_read_b128 v[2:5], v0 offset:320
	ds_read_b128 v[6:9], v0 offset:352
	s_waitcnt lgkmcnt(1)
	v_mfma_f32_32x32x16_bf16 v[80:95], v[2:5], v[132:135], v[80:95]
	s_waitcnt lgkmcnt(0)
	v_mfma_f32_32x32x16_bf16 v[80:95], v[6:9], v[140:143], v[80:95]
	s_nop 11
	v_max_f32_e32 v0, v81, v81
	v_max_f32_e32 v2, v80, v80
	v_max_f32_e32 v0, v2, v0
	v_max3_f32 v0, v0, v82, v83
	v_max3_f32 v0, v0, v84, v85
	v_max3_f32 v0, v0, v86, v87
	v_max3_f32 v0, v0, v88, v89
	v_max3_f32 v0, v0, v90, v91
	v_max3_f32 v0, v0, v92, v93
	v_max3_f32 v0, v0, v94, v95
	ds_bpermute_b32 v2, v209, v0
	s_waitcnt lgkmcnt(0)
	v_max_f32_e32 v2, v2, v2
	v_max_f32_e32 v0, v0, v2
	v_mul_f32_e32 v0, 0x3dd53b94, v0
	v_cmp_gt_f32_e32 vcc, v0, v198
	s_cbranch_vccz .LBB0_684
	v_max_f32_e32 v0, v0, v0
	v_max_f32_e32 v2, v198, v198
	v_max_f32_e32 v2, v2, v0
	v_sub_f32_e32 v0, v198, v2
	v_exp_f32_e32 v0, v0
	v_mov_b32_e32 v198, v2
	v_mul_f32_e32 v78, v78, v0
	v_mul_f32_e32 v79, v79, v0
	v_mul_f32_e32 v76, v76, v0
	v_mul_f32_e32 v77, v77, v0
	v_mul_f32_e32 v74, v74, v0
	v_mul_f32_e32 v75, v75, v0
	v_mul_f32_e32 v72, v72, v0
	v_mul_f32_e32 v73, v73, v0
	v_mul_f32_e32 v70, v70, v0
	v_mul_f32_e32 v71, v71, v0
	v_mul_f32_e32 v68, v68, v0
	v_mul_f32_e32 v69, v69, v0
	v_mul_f32_e32 v66, v66, v0
	v_mul_f32_e32 v67, v67, v0
	v_mul_f32_e32 v64, v64, v0
	v_mul_f32_e32 v65, v65, v0
	v_mul_f32_e32 v62, v62, v0
	v_mul_f32_e32 v63, v63, v0
	v_mul_f32_e32 v60, v60, v0
	v_mul_f32_e32 v61, v61, v0
	v_mul_f32_e32 v58, v58, v0
	v_mul_f32_e32 v59, v59, v0
	v_mul_f32_e32 v56, v56, v0
	v_mul_f32_e32 v57, v57, v0
	v_mul_f32_e32 v54, v54, v0
	v_mul_f32_e32 v55, v55, v0
	v_mul_f32_e32 v52, v52, v0
	v_mul_f32_e32 v53, v53, v0
	v_mul_f32_e32 v50, v50, v0
	v_mul_f32_e32 v51, v51, v0
	v_mul_f32_e32 v48, v48, v0
	v_mul_f32_e32 v49, v49, v0
	v_mul_f32_e32 v46, v46, v0
	v_mul_f32_e32 v47, v47, v0
	v_mul_f32_e32 v44, v44, v0
	v_mul_f32_e32 v45, v45, v0
	v_mul_f32_e32 v42, v42, v0
	v_mul_f32_e32 v43, v43, v0
	v_mul_f32_e32 v40, v40, v0
	v_mul_f32_e32 v41, v41, v0
	v_mul_f32_e32 v38, v38, v0
	v_mul_f32_e32 v39, v39, v0
	v_mul_f32_e32 v36, v36, v0
	v_mul_f32_e32 v37, v37, v0
	v_mul_f32_e32 v34, v34, v0
	v_mul_f32_e32 v35, v35, v0
	v_mul_f32_e32 v32, v32, v0
	v_mul_f32_e32 v33, v33, v0
	v_mul_f32_e32 v30, v30, v0
	v_mul_f32_e32 v31, v31, v0
	v_mul_f32_e32 v28, v28, v0
	v_mul_f32_e32 v29, v29, v0
	v_mul_f32_e32 v26, v26, v0
	v_mul_f32_e32 v27, v27, v0
	v_mul_f32_e32 v24, v24, v0
	v_mul_f32_e32 v25, v25, v0
	v_mul_f32_e32 v22, v22, v0
	v_mul_f32_e32 v23, v23, v0
	v_mul_f32_e32 v20, v20, v0
	v_mul_f32_e32 v21, v21, v0
	v_mul_f32_e32 v18, v18, v0
	v_mul_f32_e32 v19, v19, v0
	v_mul_f32_e32 v16, v16, v0
	v_mul_f32_e32 v17, v17, v0
	v_mul_f32_e32 v193, v193, v0
	s_branch .LBB0_684

.LBB0_1018:
	v_max_f32_e32 v2, v2, v2
	v_max_f32_e32 v3, v180, v180
	v_max_f32_e32 v2, v3, v2
	v_sub_f32_e32 v3, v180, v2
	v_exp_f32_e32 v4, v3
	v_mov_b32_e32 v180, v2
	v_mul_f32_e32 v78, v78, v4
	v_mul_f32_e32 v79, v79, v4
	v_mul_f32_e32 v76, v76, v4
	v_mul_f32_e32 v77, v77, v4
	v_mul_f32_e32 v74, v74, v4
	v_mul_f32_e32 v75, v75, v4
	v_mul_f32_e32 v72, v72, v4
	v_mul_f32_e32 v73, v73, v4
	v_mul_f32_e32 v70, v70, v4
	v_mul_f32_e32 v71, v71, v4
	v_mul_f32_e32 v68, v68, v4
	v_mul_f32_e32 v69, v69, v4
	v_mul_f32_e32 v66, v66, v4
	v_mul_f32_e32 v67, v67, v4
	v_mul_f32_e32 v64, v64, v4
	v_mul_f32_e32 v65, v65, v4
	v_mul_f32_e32 v62, v62, v4
	v_mul_f32_e32 v63, v63, v4
	v_mul_f32_e32 v60, v60, v4
	v_mul_f32_e32 v61, v61, v4
	v_mul_f32_e32 v58, v58, v4
	v_mul_f32_e32 v59, v59, v4
	v_mul_f32_e32 v56, v56, v4
	v_mul_f32_e32 v57, v57, v4
	v_mul_f32_e32 v54, v54, v4
	v_mul_f32_e32 v55, v55, v4
	v_mul_f32_e32 v52, v52, v4
	v_mul_f32_e32 v53, v53, v4
	v_mul_f32_e32 v50, v50, v4
	v_mul_f32_e32 v51, v51, v4
	v_mul_f32_e32 v48, v48, v4
	v_mul_f32_e32 v49, v49, v4
	v_mul_f32_e32 v46, v46, v4
	v_mul_f32_e32 v47, v47, v4
	v_mul_f32_e32 v44, v44, v4
	v_mul_f32_e32 v45, v45, v4
	v_mul_f32_e32 v42, v42, v4
	v_mul_f32_e32 v43, v43, v4
	v_mul_f32_e32 v40, v40, v4
	v_mul_f32_e32 v41, v41, v4
	v_mul_f32_e32 v38, v38, v4
	v_mul_f32_e32 v39, v39, v4
	v_mul_f32_e32 v36, v36, v4
	v_mul_f32_e32 v37, v37, v4
	v_mul_f32_e32 v34, v34, v4
	v_mul_f32_e32 v35, v35, v4
	v_mul_f32_e32 v32, v32, v4
	v_mul_f32_e32 v33, v33, v4
	v_mul_f32_e32 v30, v30, v4
	v_mul_f32_e32 v31, v31, v4
	v_mul_f32_e32 v28, v28, v4
	v_mul_f32_e32 v29, v29, v4
	v_mul_f32_e32 v26, v26, v4
	v_mul_f32_e32 v27, v27, v4
	v_mul_f32_e32 v24, v24, v4
	v_mul_f32_e32 v25, v25, v4
	v_mul_f32_e32 v22, v22, v4
	v_mul_f32_e32 v23, v23, v4
	v_mul_f32_e32 v20, v20, v4
	v_mul_f32_e32 v21, v21, v4
	v_mul_f32_e32 v18, v18, v4
	v_mul_f32_e32 v19, v19, v4
	v_mul_f32_e32 v16, v16, v4
	v_mul_f32_e32 v17, v17, v4
	v_mul_f32_e32 v1, v1, v4
.LBB0_1019:
	v_mov_b32_e32 v3, v180
	v_fma_f32 v4, v80, s18, -v2
	v_fma_f32 v5, v81, s18, -v3
	v_fma_f32 v8, v86, s18, -v2
	v_fma_f32 v9, v87, s18, -v3
	v_exp_f32_e32 v196, v4
	v_exp_f32_e32 v197, v5
	v_fma_f32 v4, v82, s18, -v2
	v_fma_f32 v5, v83, s18, -v3
	v_exp_f32_e32 v210, v8
	v_exp_f32_e32 v206, v4
	v_exp_f32_e32 v207, v5
	v_fma_f32 v4, v84, s18, -v2
	v_fma_f32 v5, v85, s18, -v3
	v_exp_f32_e32 v211, v9
	v_exp_f32_e32 v208, v4
	v_exp_f32_e32 v209, v5
	ds_read_b128 v[4:7], v194 offset:9280
	ds_read_b128 v[12:15], v194 offset:9312
	v_cvt_pk_bf16_f32 v8, v196, v197
	v_cvt_pk_bf16_f32 v9, v206, v207
	v_cvt_pk_bf16_f32 v10, v208, v209
	v_cvt_pk_bf16_f32 v11, v210, v211
	v_fma_f32 v84, v88, s18, -v2
	v_fma_f32 v85, v89, s18, -v3
	v_lshl_add_u64 v[178:179], v[178:179], 0, s[20:21]
	s_waitcnt lgkmcnt(1)
	v_mfma_f32_32x32x16_bf16 v[64:79], v[4:7], v[8:11], v[64:79]
	ds_read_b128 v[4:7], v194 offset:13888
	ds_read_b128 v[80:83], v194 offset:13920
	v_exp_f32_e32 v88, v84
	v_exp_f32_e32 v89, v85
	v_lshl_add_u64 v[176:177], v[176:177], 0, s[20:21]
	v_lshl_add_u64 v[174:175], v[174:175], 0, s[20:21]
	v_lshl_add_u64 v[172:173], v[172:173], 0, s[20:21]
	s_cmp_eq_u32 s31, s0
	s_waitcnt lgkmcnt(1)
	v_mfma_f32_32x32x16_bf16 v[48:63], v[4:7], v[8:11], v[48:63]
	ds_read_b128 v[4:7], v194 offset:18496
	ds_read_b128 v[84:87], v194 offset:23104
	ds_read_b128 v[202:205], v194 offset:18528
	v_lshl_add_u64 v[170:171], v[170:171], 0, s[22:23]
	s_waitcnt lgkmcnt(2)
	v_mfma_f32_32x32x16_bf16 v[32:47], v[4:7], v[8:11], v[32:47]
	v_fma_f32 v4, v90, s18, -v2
	v_fma_f32 v5, v91, s18, -v3
	v_exp_f32_e32 v90, v4
	v_exp_f32_e32 v91, v5
	v_fma_f32 v4, v92, s18, -v2
	v_fma_f32 v5, v93, s18, -v3
	v_fma_f32 v2, v94, s18, -v2
	v_fma_f32 v3, v95, s18, -v3
	v_exp_f32_e32 v92, v4
	v_exp_f32_e32 v93, v5
	ds_read_b128 v[4:7], v194 offset:23136
	s_waitcnt lgkmcnt(2)
	v_mfma_f32_32x32x16_bf16 v[16:31], v[84:87], v[8:11], v[16:31]
	v_exp_f32_e32 v2, v2
	v_exp_f32_e32 v3, v3
	v_cvt_pk_bf16_f32 v8, v88, v89
	v_cvt_pk_bf16_f32 v9, v90, v91
	v_cvt_pk_bf16_f32 v10, v92, v93
	v_cvt_pk_bf16_f32 v11, v2, v3
	s_nop 1
	v_mfma_f32_32x32x16_bf16 v[64:79], v[12:15], v[8:11], v[64:79]
	v_add_f32_e64 v12, v196, 0
	v_add_f32_e64 v13, v197, 0
	v_add_f32_e64 v12, v206, v12
	v_add_f32_e64 v13, v207, v13
	v_add_f32_e64 v12, v208, v12
	v_add_f32_e64 v13, v209, v13
	v_add_f32_e32 v12, v210, v12
	v_add_f32_e32 v13, v211, v13
	v_mfma_f32_32x32x16_bf16 v[48:63], v[80:83], v[8:11], v[48:63]
	v_add_f32_e64 v12, v88, v12
	v_add_f32_e64 v13, v89, v13
	v_add_f32_e64 v12, v90, v12
	v_add_f32_e64 v13, v91, v13
	v_add_f32_e64 v12, v92, v12
	v_add_f32_e64 v13, v93, v13
	v_add_f32_e32 v2, v2, v12
	v_add_f32_e32 v3, v3, v13
	s_waitcnt lgkmcnt(1)
	v_mfma_f32_32x32x16_bf16 v[32:47], v[202:205], v[8:11], v[32:47]
	v_add_f32_e32 v2, v2, v3
	v_add_f32_e32 v196, v1, v2
	s_waitcnt lgkmcnt(0)
	v_mfma_f32_32x32x16_bf16 v[16:31], v[4:7], v[8:11], v[16:31]
	s_cbranch_scc1 .LBB0_1026

.LBB0_1022:
	ds_read_b128 v[2:5], v193
	ds_read_b128 v[6:9], v193 offset:32
	s_waitcnt lgkmcnt(1)
	v_mfma_f32_32x32x16_bf16 v[80:95], v[2:5], v[96:99], 0
	s_waitcnt lgkmcnt(0)
	v_mfma_f32_32x32x16_bf16 v[80:95], v[6:9], v[100:103], v[80:95]
	ds_read_b128 v[2:5], v193 offset:64
	ds_read_b128 v[6:9], v193 offset:96
	s_waitcnt lgkmcnt(1)
	v_mfma_f32_32x32x16_bf16 v[80:95], v[2:5], v[104:107], v[80:95]
	s_waitcnt lgkmcnt(0)
	v_mfma_f32_32x32x16_bf16 v[80:95], v[6:9], v[108:111], v[80:95]
	s_nop 11
	v_max_f32_e32 v1, v81, v81
	v_max_f32_e32 v2, v80, v80
	v_max_f32_e32 v1, v2, v1
	v_max3_f32 v1, v1, v82, v83
	v_max3_f32 v1, v1, v84, v85
	v_max3_f32 v1, v1, v86, v87
	v_max3_f32 v1, v1, v88, v89
	v_max3_f32 v1, v1, v90, v91
	v_max3_f32 v1, v1, v92, v93
	v_max3_f32 v1, v1, v94, v95
	ds_bpermute_b32 v2, v184, v1
	s_waitcnt lgkmcnt(0)
	v_max_f32_e32 v2, v2, v2
	v_max_f32_e32 v1, v1, v2
	v_mul_f32_e32 v1, 0x3e38aa3b, v1
	v_cmp_gt_f32_e32 vcc, v1, v180
	s_cbranch_vccz .LBB0_1024
	v_max_f32_e32 v1, v1, v1
	v_max_f32_e32 v2, v180, v180
	v_max_f32_e32 v1, v2, v1
	v_sub_f32_e32 v2, v180, v1
	v_exp_f32_e32 v2, v2
	v_mov_b32_e32 v180, v1
	v_mul_f32_e32 v78, v78, v2
	v_mul_f32_e32 v79, v79, v2
	v_mul_f32_e32 v76, v76, v2
	v_mul_f32_e32 v77, v77, v2
	v_mul_f32_e32 v74, v74, v2
	v_mul_f32_e32 v75, v75, v2
	v_mul_f32_e32 v72, v72, v2
	v_mul_f32_e32 v73, v73, v2
	v_mul_f32_e32 v70, v70, v2
	v_mul_f32_e32 v71, v71, v2
	v_mul_f32_e32 v68, v68, v2
	v_mul_f32_e32 v69, v69, v2
	v_mul_f32_e32 v66, v66, v2
	v_mul_f32_e32 v67, v67, v2
	v_mul_f32_e32 v64, v64, v2
	v_mul_f32_e32 v65, v65, v2
	v_mul_f32_e32 v62, v62, v2
	v_mul_f32_e32 v63, v63, v2
	v_mul_f32_e32 v60, v60, v2
	v_mul_f32_e32 v61, v61, v2
	v_mul_f32_e32 v58, v58, v2
	v_mul_f32_e32 v59, v59, v2
	v_mul_f32_e32 v56, v56, v2
	v_mul_f32_e32 v57, v57, v2
	v_mul_f32_e32 v54, v54, v2
	v_mul_f32_e32 v55, v55, v2
	v_mul_f32_e32 v52, v52, v2
	v_mul_f32_e32 v53, v53, v2
	v_mul_f32_e32 v50, v50, v2
	v_mul_f32_e32 v51, v51, v2
	v_mul_f32_e32 v48, v48, v2
	v_mul_f32_e32 v49, v49, v2
	v_mul_f32_e32 v46, v46, v2
	v_mul_f32_e32 v47, v47, v2
	v_mul_f32_e32 v44, v44, v2
	v_mul_f32_e32 v45, v45, v2
	v_mul_f32_e32 v42, v42, v2
	v_mul_f32_e32 v43, v43, v2
	v_mul_f32_e32 v40, v40, v2
	v_mul_f32_e32 v41, v41, v2
	v_mul_f32_e32 v38, v38, v2
	v_mul_f32_e32 v39, v39, v2
	v_mul_f32_e32 v36, v36, v2
	v_mul_f32_e32 v37, v37, v2
	v_mul_f32_e32 v34, v34, v2
	v_mul_f32_e32 v35, v35, v2
	v_mul_f32_e32 v32, v32, v2
	v_mul_f32_e32 v33, v33, v2
	v_mul_f32_e32 v30, v30, v2
	v_mul_f32_e32 v31, v31, v2
	v_mul_f32_e32 v28, v28, v2
	v_mul_f32_e32 v29, v29, v2
	v_mul_f32_e32 v26, v26, v2
	v_mul_f32_e32 v27, v27, v2
	v_mul_f32_e32 v24, v24, v2
	v_mul_f32_e32 v25, v25, v2
	v_mul_f32_e32 v22, v22, v2
	v_mul_f32_e32 v23, v23, v2
	v_mul_f32_e32 v20, v20, v2
	v_mul_f32_e32 v21, v21, v2
	v_mul_f32_e32 v18, v18, v2
	v_mul_f32_e32 v19, v19, v2
	v_mul_f32_e32 v16, v16, v2
	v_mul_f32_e32 v17, v17, v2
	v_mul_f32_e32 v196, v196, v2
.LBB0_1024:
	v_fma_f32 v2, v80, s18, -v180
	v_fma_f32 v3, v81, s18, -v180
	v_fma_f32 v6, v86, s18, -v180
	v_fma_f32 v7, v87, s18, -v180
	v_exp_f32_e32 v214, v2
	v_exp_f32_e32 v215, v3
	v_fma_f32 v2, v82, s18, -v180
	v_fma_f32 v3, v83, s18, -v180
	v_exp_f32_e32 v220, v6
	v_exp_f32_e32 v216, v2
	v_exp_f32_e32 v217, v3
	v_fma_f32 v2, v84, s18, -v180
	v_fma_f32 v3, v85, s18, -v180
	v_exp_f32_e32 v221, v7
	v_exp_f32_e32 v218, v2
	v_exp_f32_e32 v219, v3
	ds_read_b128 v[2:5], v194 offset:9216
	ds_read_b128 v[10:13], v194 offset:9248
	v_cvt_pk_bf16_f32 v6, v214, v215
	v_cvt_pk_bf16_f32 v7, v216, v217
	v_cvt_pk_bf16_f32 v8, v218, v219
	v_cvt_pk_bf16_f32 v9, v220, v221
	v_fma_f32 v14, v88, s18, -v180
	v_fma_f32 v15, v89, s18, -v180
	s_waitcnt lgkmcnt(1)
	v_mfma_f32_32x32x16_bf16 v[64:79], v[2:5], v[6:9], v[64:79]
	ds_read_b128 v[2:5], v194 offset:13824
	ds_read_b128 v[202:205], v194 offset:13856
	v_exp_f32_e32 v222, v14
	v_exp_f32_e32 v223, v15
	s_waitcnt lgkmcnt(1)
	v_mfma_f32_32x32x16_bf16 v[48:63], v[2:5], v[6:9], v[48:63]
	ds_read_b128 v[2:5], v194 offset:18432
	ds_read_b128 v[80:83], v194 offset:23040
	ds_read_b128 v[206:209], v194 offset:18464
	ds_read_b128 v[210:213], v194 offset:23072
	s_waitcnt lgkmcnt(3)
	v_mfma_f32_32x32x16_bf16 v[32:47], v[2:5], v[6:9], v[32:47]
	v_fma_f32 v4, v92, s18, -v180
	v_fma_f32 v5, v93, s18, -v180
	v_fma_f32 v2, v90, s18, -v180
	v_fma_f32 v3, v91, s18, -v180
	v_exp_f32_e32 v224, v4
	v_exp_f32_e32 v225, v5
	v_fma_f32 v4, v94, s18, -v180
	v_fma_f32 v5, v95, s18, -v180
	v_exp_f32_e32 v2, v2
	v_exp_f32_e32 v3, v3
	v_exp_f32_e32 v226, v4
	v_exp_f32_e32 v227, v5
	s_waitcnt lgkmcnt(2)
	v_mfma_f32_32x32x16_bf16 v[16:31], v[80:83], v[6:9], v[16:31]
	v_cvt_pk_bf16_f32 v4, v222, v223
	v_cvt_pk_bf16_f32 v5, v2, v3
	v_cvt_pk_bf16_f32 v6, v224, v225
	v_cvt_pk_bf16_f32 v7, v226, v227
	s_nop 1
	v_mfma_f32_32x32x16_bf16 v[64:79], v[10:13], v[4:7], v[64:79]
	ds_read_b128 v[8:11], v193 offset:4608
	ds_read_b128 v[12:15], v193 offset:4640
	s_waitcnt lgkmcnt(1)
	v_mfma_f32_32x32x16_bf16 v[80:95], v[8:11], v[96:99], 0
	s_waitcnt lgkmcnt(0)
	v_mfma_f32_32x32x16_bf16 v[80:95], v[12:15], v[100:103], v[80:95]
	ds_read_b128 v[8:11], v193 offset:4672
	ds_read_b128 v[12:15], v193 offset:4704
	s_waitcnt lgkmcnt(1)
	v_mfma_f32_32x32x16_bf16 v[80:95], v[8:11], v[104:107], v[80:95]
	v_add_f32_e64 v8, v214, 0
	v_add_f32_e64 v9, v215, 0
	v_add_f32_e64 v8, v216, v8
	v_add_f32_e64 v9, v217, v9
	v_add_f32_e64 v8, v218, v8
	v_add_f32_e64 v9, v219, v9
	v_add_f32_e32 v8, v220, v8
	v_add_f32_e32 v9, v221, v9
	s_waitcnt lgkmcnt(0)
	v_mfma_f32_32x32x16_bf16 v[80:95], v[12:15], v[108:111], v[80:95]
	v_add_f32_e64 v8, v222, v8
	v_add_f32_e64 v9, v223, v9
	v_add_f32_e64 v2, v2, v8
	v_add_f32_e64 v3, v3, v9
	v_add_f32_e64 v2, v224, v2
	v_add_f32_e64 v3, v225, v3
	s_nop 5
	v_max_f32_e32 v1, v81, v81
	v_max_f32_e32 v8, v80, v80
	v_max_f32_e32 v1, v8, v1
	v_max3_f32 v1, v1, v82, v83
	v_max3_f32 v1, v1, v84, v85
	v_max3_f32 v1, v1, v86, v87
	v_max3_f32 v1, v1, v88, v89
	v_max3_f32 v1, v1, v90, v91
	v_max3_f32 v1, v1, v92, v93
	v_max3_f32 v8, v1, v94, v95
	ds_bpermute_b32 v9, v184, v8
	v_mfma_f32_32x32x16_bf16 v[48:63], v[202:205], v[4:7], v[48:63]
	v_add_f32_e64 v2, v226, v2
	v_add_f32_e64 v3, v227, v3
	v_add_f32_e32 v1, v2, v3
	s_waitcnt lgkmcnt(0)
	v_max_f32_e32 v2, v9, v9
	v_max_f32_e32 v2, v8, v2
	v_mul_f32_e32 v2, 0x3e38aa3b, v2
	v_add_f32_e32 v1, v196, v1
	v_mfma_f32_32x32x16_bf16 v[32:47], v[206:209], v[4:7], v[32:47]
	v_cmp_gt_f32_e32 vcc, v2, v180
	v_mfma_f32_32x32x16_bf16 v[16:31], v[210:213], v[4:7], v[16:31]
	s_cbranch_vccnz .LBB0_1018
	v_mov_b64_e32 v[2:3], v[180:181]
	s_branch .LBB0_1019
.LBB0_1026:
	ds_bpermute_b32 v1, v184, v196
	s_mov_b64 s[28:29], -1
	s_waitcnt lgkmcnt(0)
	v_add_f32_e32 v1, v196, v1
	v_div_scale_f32 v2, s[0:1], v1, v1, 1.0
	v_rcp_f32_e32 v3, v2
	v_div_scale_f32 v4, vcc, 1.0, v1, 1.0
	s_and_b64 s[0:1], exec, s[26:27]
	v_fma_f32 v5, -v2, v3, 1.0
	v_fmac_f32_e32 v3, v5, v3
	v_mul_f32_e32 v5, v4, v3
	v_fma_f32 v6, -v2, v5, v4
	v_fmac_f32_e32 v5, v6, v3
	v_fma_f32 v2, -v2, v5, v4
	v_div_fmas_f32 v2, v2, v3, v5
	v_div_fixup_f32 v6, v2, v1, 1.0
	s_mov_b64 vcc, s[0:1]
	s_cbranch_vccz .LBB0_1028
	v_mov_b32_e32 v1, s11
	ds_read_b64 v[2:3], v1
	s_waitcnt lgkmcnt(0)
	v_readfirstlane_b32 s0, v2
	v_readfirstlane_b32 s1, v3
	s_nop 4
	global_load_dword v1, v191, s[0:1]
	global_load_dword v2, v191, s[0:1] offset:256
	global_load_dword v3, v191, s[0:1] offset:512
	global_load_dword v4, v191, s[0:1] offset:768
	s_waitcnt vmcnt(2)
	v_mul_f32_e32 v5, v1, v2
	ds_bpermute_b32 v12, v185, v5
	s_waitcnt vmcnt(0)
	v_mul_f32_e32 v7, v3, v4
	ds_bpermute_b32 v7, v185, v7
	s_waitcnt lgkmcnt(1)
	v_fmac_f32_e32 v12, v1, v2
	ds_bpermute_b32 v1, v186, v12
	s_waitcnt lgkmcnt(1)
	v_fmac_f32_e32 v7, v3, v4
	ds_bpermute_b32 v13, v186, v7
	ds_read2st64_b32 v[2:3], v139 offset0:108 offset1:109
	ds_read2st64_b32 v[4:5], v139 offset0:110 offset1:111
	ds_read2st64_b32 v[8:9], v139 offset0:112 offset1:113
	ds_read2st64_b32 v[10:11], v139 offset0:114 offset1:115
	s_waitcnt lgkmcnt(5)
	v_add_f32_e32 v1, v12, v1
	ds_bpermute_b32 v12, v187, v1
	s_waitcnt lgkmcnt(5)
	v_add_f32_e32 v7, v7, v13
	ds_bpermute_b32 v13, v187, v7
	s_waitcnt lgkmcnt(5)
	v_lshlrev_b32_e32 v96, 16, v2
	v_and_b32_e32 v97, 0xffff0000, v2
	s_waitcnt lgkmcnt(1)
	v_add_f32_e32 v1, v1, v12
	v_lshlrev_b32_e32 v98, 16, v3
	s_waitcnt lgkmcnt(0)
	v_add_f32_e32 v2, v7, v13
	ds_bpermute_b32 v7, v188, v1
	ds_bpermute_b32 v12, v188, v2
	v_and_b32_e32 v99, 0xffff0000, v3
	v_lshlrev_b32_e32 v100, 16, v4
	v_and_b32_e32 v101, 0xffff0000, v4
	s_waitcnt lgkmcnt(1)
	v_add_f32_e32 v1, v1, v7
	s_waitcnt lgkmcnt(0)
	v_add_f32_e32 v2, v2, v12
	ds_bpermute_b32 v3, v189, v1
	ds_bpermute_b32 v4, v189, v2
	v_lshlrev_b32_e32 v7, 16, v5
	v_and_b32_e32 v102, 0xffff0000, v5
	v_lshlrev_b32_e32 v103, 16, v8
	s_waitcnt lgkmcnt(1)
	v_add_f32_e32 v1, v1, v3
	s_waitcnt lgkmcnt(0)
	v_add_f32_e32 v2, v2, v4
	ds_bpermute_b32 v3, v184, v1
	ds_bpermute_b32 v4, v184, v2
	v_and_b32_e32 v104, 0xffff0000, v8
	v_lshlrev_b32_e32 v105, 16, v9
	v_and_b32_e32 v9, 0xffff0000, v9
	s_waitcnt lgkmcnt(1)
	v_add_f32_e32 v1, v1, v3
	s_waitcnt lgkmcnt(0)
	v_add_f32_e32 v2, v2, v4
	v_mul_f32_e32 v1, 0x3fb8aa3b, v1
	v_mul_f32_e32 v2, 0x3fb8aa3b, v2
	v_exp_f32_e32 v1, v1
	v_exp_f32_e32 v2, v2
	v_lshlrev_b32_e32 v106, 16, v10
	v_and_b32_e32 v107, 0xffff0000, v10
	v_lshlrev_b32_e32 v108, 16, v11
	v_sub_f32_e32 v1, v1, v2
	v_add_f32_e32 v1, 0x3eb60549, v1
	v_mul_f32_e32 v8, v6, v1
	v_and_b32_e32 v109, 0xffff0000, v11
	ds_read2st64_b32 v[2:3], v139 offset0:116 offset1:117
	ds_read2st64_b32 v[4:5], v139 offset0:118 offset1:119
	ds_read2st64_b32 v[10:11], v139 offset0:120 offset1:121
	ds_read2st64_b32 v[12:13], v139 offset0:122 offset1:123
	s_waitcnt lgkmcnt(3)
	v_lshlrev_b32_e32 v110, 16, v2
	v_and_b32_e32 v111, 0xffff0000, v2
	v_lshlrev_b32_e32 v112, 16, v3
	v_and_b32_e32 v113, 0xffff0000, v3
	s_waitcnt lgkmcnt(2)
	v_lshlrev_b32_e32 v114, 16, v4
	v_and_b32_e32 v115, 0xffff0000, v4
	v_lshlrev_b32_e32 v116, 16, v5
	v_and_b32_e32 v117, 0xffff0000, v5
	s_waitcnt lgkmcnt(1)
	v_lshlrev_b32_e32 v118, 16, v10
	v_and_b32_e32 v119, 0xffff0000, v10
	v_lshlrev_b32_e32 v120, 16, v11
	v_and_b32_e32 v121, 0xffff0000, v11
	s_waitcnt lgkmcnt(0)
	v_lshlrev_b32_e32 v122, 16, v12
	v_and_b32_e32 v123, 0xffff0000, v12
	v_lshlrev_b32_e32 v124, 16, v13
	v_and_b32_e32 v125, 0xffff0000, v13
	ds_read2st64_b32 v[2:3], v139 offset0:124 offset1:125
	ds_read2st64_b32 v[4:5], v139 offset0:126 offset1:127
	ds_read2st64_b32 v[10:11], v139 offset0:128 offset1:129
	ds_read2st64_b32 v[12:13], v139 offset0:130 offset1:131
	s_waitcnt lgkmcnt(3)
	v_lshlrev_b32_e32 v126, 16, v2
	v_and_b32_e32 v127, 0xffff0000, v2
	v_lshlrev_b32_e32 v128, 16, v3
	v_and_b32_e32 v129, 0xffff0000, v3
	s_waitcnt lgkmcnt(2)
	v_lshlrev_b32_e32 v130, 16, v4
	v_and_b32_e32 v131, 0xffff0000, v4
	v_lshlrev_b32_e32 v132, 16, v5
	v_and_b32_e32 v133, 0xffff0000, v5
	s_waitcnt lgkmcnt(1)
	v_lshlrev_b32_e32 v134, 16, v10
	v_and_b32_e32 v135, 0xffff0000, v10
	v_lshlrev_b32_e32 v170, 16, v11
	v_and_b32_e32 v171, 0xffff0000, v11
	s_waitcnt lgkmcnt(0)
	v_lshlrev_b32_e32 v172, 16, v12
	v_and_b32_e32 v173, 0xffff0000, v12
	v_lshlrev_b32_e32 v174, 16, v13
	v_and_b32_e32 v175, 0xffff0000, v13
	ds_read2st64_b32 v[2:3], v139 offset0:132 offset1:133
	ds_read2st64_b32 v[4:5], v139 offset0:134 offset1:135
	ds_read2st64_b32 v[10:11], v139 offset0:136 offset1:137
	ds_read_b32 v1, v139 offset:35328
	v_mov_b32_e32 v12, v20
	s_waitcnt lgkmcnt(3)
	v_lshlrev_b32_e32 v176, 16, v2
	v_and_b32_e32 v177, 0xffff0000, v2
	v_lshlrev_b32_e32 v178, 16, v3
	v_and_b32_e32 v179, 0xffff0000, v3
	s_waitcnt lgkmcnt(2)
	v_lshlrev_b32_e32 v3, 16, v5
	v_lshlrev_b32_e32 v2, 16, v4
	v_mov_b32_e32 v13, v22
	v_mul_f32_e32 v82, v12, v8
	v_mul_f32_e32 v83, v13, v8
	v_fma_f32 v2, -v12, v8, v2
	v_fma_f32 v3, -v13, v8, v3
	v_and_b32_e32 v5, 0xffff0000, v5
	v_and_b32_e32 v4, 0xffff0000, v4
	v_mov_b32_e32 v12, v21
	v_mov_b32_e32 v13, v23
	v_fma_f32 v4, -v12, v8, v4
	v_fma_f32 v5, -v13, v8, v5
	v_mul_f32_e32 v84, v12, v8
	v_mul_f32_e32 v85, v13, v8
	v_mul_f32_e32 v4, v4, v4
	v_mul_f32_e32 v5, v5, v5
	ds_read_b32 v12, v195 offset:27648
	v_fma_f32 v86, v2, v2, v4
	v_fma_f32 v87, v3, v3, v5
	s_waitcnt lgkmcnt(2)
	v_lshlrev_b32_e32 v3, 16, v11
	v_lshlrev_b32_e32 v2, 16, v10
	v_mov_b32_e32 v4, v24
	v_mov_b32_e32 v5, v26
	v_mul_f32_e32 v14, v4, v8
	v_mul_f32_e32 v15, v5, v8
	v_fma_f32 v2, -v4, v8, v2
	v_fma_f32 v3, -v5, v8, v3
	v_and_b32_e32 v5, 0xffff0000, v11
	v_and_b32_e32 v4, 0xffff0000, v10
	v_mov_b32_e32 v10, v25
	v_mov_b32_e32 v11, v27
	v_fma_f32 v4, -v10, v8, v4
	v_fma_f32 v5, -v11, v8, v5
	v_mul_f32_e32 v80, v10, v8
	v_mul_f32_e32 v81, v11, v8
	v_mul_f32_e32 v4, v4, v4
	v_mul_f32_e32 v5, v5, v5
	v_mov_b32_e32 v90, v29
	v_fma_f32 v88, v2, v2, v4
	v_fma_f32 v89, v3, v3, v5
	s_waitcnt lgkmcnt(0)
	v_lshlrev_b32_e32 v3, 16, v12
	v_lshlrev_b32_e32 v2, 16, v1
	v_mov_b32_e32 v4, v28
	v_mov_b32_e32 v5, v30
	v_mul_f32_e32 v10, v4, v8
	v_mul_f32_e32 v11, v5, v8
	v_fma_f32 v2, -v4, v8, v2
	v_fma_f32 v3, -v5, v8, v3
	v_and_b32_e32 v5, 0xffff0000, v12
	v_and_b32_e32 v4, 0xffff0000, v1
	v_mov_b32_e32 v91, v31
	v_fma_f32 v4, -v90, v8, v4
	v_fma_f32 v5, -v91, v8, v5
	v_mul_f32_e32 v12, v90, v8
	v_mul_f32_e32 v13, v91, v8
	v_mul_f32_e32 v4, v4, v4
	v_mul_f32_e32 v5, v5, v5
	s_nop 0
	v_fma_f32 v92, v2, v2, v4
	v_fma_f32 v93, v3, v3, v5
	v_mul_f32_e32 v94, v66, v8
	v_mul_f32_e32 v95, v67, v8
	v_mov_b32_e32 v1, s19
	v_sub_f32_e32 v95, v99, v95
	v_sub_f32_e32 v94, v98, v94
	v_mul_f32_e32 v98, v95, v95
	v_fmac_f32_e32 v98, v94, v94
	v_mul_f32_e32 v94, v64, v8
	v_mul_f32_e32 v95, v65, v8
	ds_read_b64 v[2:3], v1
	v_sub_f32_e32 v95, v97, v95
	v_sub_f32_e32 v94, v96, v94
	v_mul_f32_e32 v95, v95, v95
	v_fmac_f32_e32 v95, v94, v94
	v_add_f32_e32 v96, v95, v98
	v_mul_f32_e32 v94, v70, v8
	v_mul_f32_e32 v95, v71, v8
	v_lshlrev_b32_e32 v1, 2, v140
	v_sub_f32_e32 v7, v7, v94
	v_sub_f32_e32 v94, v102, v95
	v_mul_f32_e32 v97, v94, v94
	v_mul_f32_e32 v94, v68, v8
	v_mul_f32_e32 v95, v69, v8
	v_fmac_f32_e32 v97, v7, v7
	v_sub_f32_e32 v7, v100, v94
	v_sub_f32_e32 v94, v101, v95
	v_mul_f32_e32 v94, v94, v94
	v_fmac_f32_e32 v94, v7, v7
	v_add_f32_e32 v7, v94, v96
	v_mul_f32_e32 v94, v74, v8
	v_mul_f32_e32 v95, v75, v8
	v_add_f32_e32 v7, v97, v7
	v_sub_f32_e32 v9, v9, v95
	v_sub_f32_e32 v94, v105, v94
	v_mul_f32_e32 v9, v9, v9
	v_fmac_f32_e32 v9, v94, v94
	v_mul_f32_e32 v94, v72, v8
	v_mul_f32_e32 v95, v73, v8
	s_waitcnt lgkmcnt(0)
	v_readfirstlane_b32 s0, v2
	v_sub_f32_e32 v95, v104, v95
	v_sub_f32_e32 v94, v103, v94
	v_mul_f32_e32 v95, v95, v95
	v_fmac_f32_e32 v95, v94, v94
	v_readfirstlane_b32 s1, v3
	v_add_f32_e32 v7, v95, v7
	v_mul_f32_e32 v94, v78, v8
	v_mul_f32_e32 v95, v79, v8
	v_add_f32_e32 v7, v9, v7
	v_sub_f32_e32 v9, v108, v94
	v_sub_f32_e32 v94, v109, v95
	global_load_dwordx4 v[2:5], v1, s[0:1]
	v_mul_f32_e32 v96, v94, v94
	v_mul_f32_e32 v94, v76, v8
	v_mul_f32_e32 v95, v77, v8
	v_fmac_f32_e32 v96, v9, v9
	v_sub_f32_e32 v9, v106, v94
	v_sub_f32_e32 v94, v107, v95
	v_mul_f32_e32 v94, v94, v94
	v_fmac_f32_e32 v94, v9, v9
	v_add_f32_e32 v7, v94, v7
	v_mul_f32_e32 v94, v50, v8
	v_mul_f32_e32 v95, v51, v8
	v_add_f32_e32 v7, v96, v7
	v_sub_f32_e32 v9, v112, v94
	v_sub_f32_e32 v94, v113, v95
	v_mul_f32_e32 v96, v94, v94
	v_mul_f32_e32 v94, v48, v8
	v_mul_f32_e32 v95, v49, v8
	v_fmac_f32_e32 v96, v9, v9
	v_sub_f32_e32 v9, v110, v94
	v_sub_f32_e32 v94, v111, v95
	v_mul_f32_e32 v94, v94, v94
	v_fmac_f32_e32 v94, v9, v9
	v_add_f32_e32 v7, v94, v7
	v_mul_f32_e32 v94, v54, v8
	v_mul_f32_e32 v95, v55, v8
	v_add_f32_e32 v7, v96, v7
	v_sub_f32_e32 v9, v116, v94
	v_sub_f32_e32 v94, v117, v95
	v_mul_f32_e32 v96, v94, v94
	v_mul_f32_e32 v94, v52, v8
	v_mul_f32_e32 v95, v53, v8
	v_fmac_f32_e32 v96, v9, v9
	v_sub_f32_e32 v9, v114, v94
	v_sub_f32_e32 v94, v115, v95
	v_mul_f32_e32 v94, v94, v94
	v_fmac_f32_e32 v94, v9, v9
	v_add_f32_e32 v7, v94, v7
	v_mul_f32_e32 v94, v58, v8
	v_mul_f32_e32 v95, v59, v8
	v_add_f32_e32 v7, v96, v7
	v_sub_f32_e32 v9, v120, v94
	v_sub_f32_e32 v94, v121, v95
	v_mul_f32_e32 v96, v94, v94
	v_mul_f32_e32 v94, v56, v8
	v_mul_f32_e32 v95, v57, v8
	v_fmac_f32_e32 v96, v9, v9
	v_sub_f32_e32 v9, v118, v94
	v_sub_f32_e32 v94, v119, v95
	v_mul_f32_e32 v94, v94, v94
	v_fmac_f32_e32 v94, v9, v9
	v_add_f32_e32 v7, v94, v7
	v_mul_f32_e32 v94, v62, v8
	v_mul_f32_e32 v95, v63, v8
	v_add_f32_e32 v7, v96, v7
	v_sub_f32_e32 v9, v124, v94
	v_sub_f32_e32 v94, v125, v95
	v_mul_f32_e32 v96, v94, v94
	v_mul_f32_e32 v94, v60, v8
	v_mul_f32_e32 v95, v61, v8
	v_fmac_f32_e32 v96, v9, v9
	v_sub_f32_e32 v9, v122, v94
	v_sub_f32_e32 v94, v123, v95
	v_mul_f32_e32 v94, v94, v94
	v_fmac_f32_e32 v94, v9, v9
	v_add_f32_e32 v7, v94, v7
	v_mul_f32_e32 v94, v34, v8
	v_mul_f32_e32 v95, v35, v8
	v_add_f32_e32 v7, v96, v7
	v_sub_f32_e32 v9, v128, v94
	v_sub_f32_e32 v94, v129, v95
	v_mul_f32_e32 v96, v94, v94
	v_mul_f32_e32 v94, v32, v8
	v_mul_f32_e32 v95, v33, v8
	v_fmac_f32_e32 v96, v9, v9
	v_sub_f32_e32 v9, v126, v94
	v_sub_f32_e32 v94, v127, v95
	v_mul_f32_e32 v94, v94, v94
	v_fmac_f32_e32 v94, v9, v9
	v_add_f32_e32 v7, v94, v7
	v_mul_f32_e32 v94, v38, v8
	v_mul_f32_e32 v95, v39, v8
	v_add_f32_e32 v7, v96, v7
	v_sub_f32_e32 v9, v132, v94
	v_sub_f32_e32 v94, v133, v95
	v_mul_f32_e32 v96, v94, v94
	v_mul_f32_e32 v94, v36, v8
	v_mul_f32_e32 v95, v37, v8
	v_fmac_f32_e32 v96, v9, v9
	v_sub_f32_e32 v9, v130, v94
	v_sub_f32_e32 v94, v131, v95
	v_mul_f32_e32 v94, v94, v94
	v_fmac_f32_e32 v94, v9, v9
	v_add_f32_e32 v7, v94, v7
	v_mul_f32_e32 v94, v42, v8
	v_mul_f32_e32 v95, v43, v8
	v_add_f32_e32 v7, v96, v7
	v_sub_f32_e32 v9, v170, v94
	v_sub_f32_e32 v94, v171, v95
	v_mul_f32_e32 v96, v94, v94
	v_mul_f32_e32 v94, v40, v8
	v_mul_f32_e32 v95, v41, v8
	v_fmac_f32_e32 v96, v9, v9
	v_sub_f32_e32 v9, v134, v94
	v_sub_f32_e32 v94, v135, v95
	v_mul_f32_e32 v94, v94, v94
	v_fmac_f32_e32 v94, v9, v9
	v_add_f32_e32 v7, v94, v7
	v_mul_f32_e32 v94, v46, v8
	v_mul_f32_e32 v95, v47, v8
	v_add_f32_e32 v7, v96, v7
	v_sub_f32_e32 v9, v174, v94
	v_sub_f32_e32 v94, v175, v95
	v_mul_f32_e32 v96, v94, v94
	v_mul_f32_e32 v94, v44, v8
	v_mul_f32_e32 v95, v45, v8
	v_fmac_f32_e32 v96, v9, v9
	v_sub_f32_e32 v9, v172, v94
	v_sub_f32_e32 v94, v173, v95
	v_mul_f32_e32 v94, v94, v94
	v_fmac_f32_e32 v94, v9, v9
	v_add_f32_e32 v7, v94, v7
	v_mul_f32_e32 v94, v18, v8
	v_mul_f32_e32 v95, v19, v8
	v_add_f32_e32 v7, v96, v7
	v_sub_f32_e32 v9, v178, v94
	v_sub_f32_e32 v94, v179, v95
	v_mul_f32_e32 v96, v94, v94
	v_mul_f32_e32 v94, v16, v8
	v_mul_f32_e32 v95, v17, v8
	v_fmac_f32_e32 v96, v9, v9
	v_sub_f32_e32 v9, v176, v94
	v_sub_f32_e32 v94, v177, v95
	v_mul_f32_e32 v94, v94, v94
	v_fmac_f32_e32 v94, v9, v9
	v_add_f32_e32 v7, v7, v94
	v_add_f32_e32 v7, v7, v96
	v_add_f32_e32 v7, v7, v86
	v_add_f32_e32 v7, v7, v87
	v_add_f32_e32 v7, v7, v88
	v_add_f32_e32 v7, v7, v89
	v_add_f32_e32 v7, v7, v92
	v_add_f32_e32 v7, v7, v93
	ds_bpermute_b32 v9, v184, v7
	ds_read2st64_b32 v[90:91], v139 offset0:108 offset1:109
	ds_read2st64_b32 v[88:89], v139 offset0:110 offset1:111
	ds_read2st64_b32 v[92:93], v139 offset0:112 offset1:113
	ds_read2st64_b32 v[94:95], v139 offset0:114 offset1:115
	s_waitcnt lgkmcnt(4)
	v_add_f32_e32 v7, v7, v9
	v_fmamk_f32 v7, v7, 0x3c000000, v192
	v_rsq_f32_e32 v7, v7
	s_waitcnt lgkmcnt(3)
	v_lshlrev_b32_e32 v86, 16, v90
	v_and_b32_e32 v87, 0xffff0000, v90
	v_lshlrev_b32_e32 v90, 16, v91
	v_and_b32_e32 v91, 0xffff0000, v91
	v_fma_f32 v96, -v64, v8, v86
	v_fma_f32 v97, -v65, v8, v87
	v_fma_f32 v90, -v66, v8, v90
	v_fma_f32 v91, -v67, v8, v91
	v_mul_f32_e32 v86, 0x3f24fd5c, v7
	v_mul_f32_e32 v96, v96, v86
	v_mul_f32_e32 v97, v97, v86
	v_mul_f32_e32 v90, v86, v90
	v_mul_f32_e32 v91, v86, v91
	s_waitcnt vmcnt(0)
	v_mul_f32_e32 v2, v2, v96
	v_mul_f32_e32 v3, v3, v97
	v_mul_f32_e32 v4, v4, v90
	v_mul_f32_e32 v5, v5, v91
	v_cvt_pk_bf16_f32 v2, v2, v3
	v_cvt_pk_bf16_f32 v3, v4, v5
	global_store_dwordx2 v[150:151], v[2:3], off sc1
	global_load_dwordx4 v[2:5], v1, s[0:1] offset:32
	s_waitcnt lgkmcnt(2)
	v_lshlrev_b32_e32 v90, 16, v88
	v_and_b32_e32 v91, 0xffff0000, v88
	v_lshlrev_b32_e32 v88, 16, v89
	v_and_b32_e32 v89, 0xffff0000, v89
	v_fma_f32 v90, -v68, v8, v90
	v_fma_f32 v91, -v69, v8, v91
	v_fma_f32 v88, -v70, v8, v88
	v_fma_f32 v89, -v71, v8, v89
	v_mul_f32_e32 v90, v86, v90
	v_mul_f32_e32 v91, v86, v91
	v_mul_f32_e32 v88, v86, v88
	v_mul_f32_e32 v89, v86, v89
	s_waitcnt vmcnt(0)
	v_mul_f32_e32 v2, v2, v90
	v_mul_f32_e32 v3, v3, v91
	v_mul_f32_e32 v4, v4, v88
	v_mul_f32_e32 v5, v5, v89
	v_cvt_pk_bf16_f32 v2, v2, v3
	v_cvt_pk_bf16_f32 v3, v4, v5
	global_store_dwordx2 v[150:151], v[2:3], off offset:16 sc1
	global_load_dwordx4 v[2:5], v1, s[0:1] offset:64
	s_waitcnt lgkmcnt(1)
	v_lshlrev_b32_e32 v88, 16, v92
	v_and_b32_e32 v89, 0xffff0000, v92
	v_lshlrev_b32_e32 v90, 16, v93
	v_and_b32_e32 v91, 0xffff0000, v93
	v_fma_f32 v88, -v72, v8, v88
	v_fma_f32 v89, -v73, v8, v89
	v_fma_f32 v90, -v74, v8, v90
	v_fma_f32 v91, -v75, v8, v91
	v_mul_f32_e32 v88, v86, v88
	v_mul_f32_e32 v89, v86, v89
	v_mul_f32_e32 v90, v86, v90
	v_mul_f32_e32 v91, v86, v91
	s_waitcnt vmcnt(0)
	v_mul_f32_e32 v2, v2, v88
	v_mul_f32_e32 v3, v3, v89
	v_mul_f32_e32 v4, v4, v90
	v_mul_f32_e32 v5, v5, v91
	v_cvt_pk_bf16_f32 v2, v2, v3
	v_cvt_pk_bf16_f32 v3, v4, v5
	global_store_dwordx2 v[150:151], v[2:3], off offset:32 sc1
	global_load_dwordx4 v[2:5], v1, s[0:1] offset:96
	s_waitcnt lgkmcnt(0)
	v_lshlrev_b32_e32 v88, 16, v94
	v_and_b32_e32 v89, 0xffff0000, v94
	v_lshlrev_b32_e32 v90, 16, v95
	v_and_b32_e32 v91, 0xffff0000, v95
	v_fma_f32 v88, -v76, v8, v88
	v_fma_f32 v89, -v77, v8, v89
	v_fma_f32 v90, -v78, v8, v90
	v_fma_f32 v91, -v79, v8, v91
	v_mul_f32_e32 v88, v86, v88
	v_mul_f32_e32 v89, v86, v89
	v_mul_f32_e32 v90, v86, v90
	v_mul_f32_e32 v91, v86, v91
	s_waitcnt vmcnt(0)
	v_mul_f32_e32 v2, v2, v88
	v_mul_f32_e32 v3, v3, v89
	v_mul_f32_e32 v4, v4, v90
	v_mul_f32_e32 v5, v5, v91
	v_cvt_pk_bf16_f32 v2, v2, v3
	v_cvt_pk_bf16_f32 v3, v4, v5
	global_store_dwordx2 v[150:151], v[2:3], off offset:48 sc1
	global_load_dwordx4 v[2:5], v1, s[0:1] offset:128
	ds_read2st64_b32 v[88:89], v139 offset0:116 offset1:117
	ds_read2st64_b32 v[90:91], v139 offset0:118 offset1:119
	ds_read2st64_b32 v[92:93], v139 offset0:120 offset1:121
	ds_read2st64_b32 v[94:95], v139 offset0:122 offset1:123
	s_waitcnt lgkmcnt(3)
	v_lshlrev_b32_e32 v96, 16, v88
	v_and_b32_e32 v97, 0xffff0000, v88
	v_lshlrev_b32_e32 v88, 16, v89
	v_and_b32_e32 v89, 0xffff0000, v89
	v_fma_f32 v96, -v48, v8, v96
	v_fma_f32 v97, -v49, v8, v97
	v_fma_f32 v88, -v50, v8, v88
	v_fma_f32 v89, -v51, v8, v89
	v_mul_f32_e32 v96, v86, v96
	v_mul_f32_e32 v97, v86, v97
	v_mul_f32_e32 v88, v86, v88
	v_mul_f32_e32 v89, v86, v89
	s_waitcnt vmcnt(0)
	v_mul_f32_e32 v2, v2, v96
	v_mul_f32_e32 v3, v3, v97
	v_mul_f32_e32 v4, v4, v88
	v_mul_f32_e32 v5, v5, v89
	v_cvt_pk_bf16_f32 v2, v2, v3
	v_cvt_pk_bf16_f32 v3, v4, v5
	global_store_dwordx2 v[150:151], v[2:3], off offset:64 sc1
	global_load_dwordx4 v[2:5], v1, s[0:1] offset:160
	s_waitcnt lgkmcnt(2)
	v_lshlrev_b32_e32 v88, 16, v90
	v_and_b32_e32 v89, 0xffff0000, v90
	v_lshlrev_b32_e32 v90, 16, v91
	v_and_b32_e32 v91, 0xffff0000, v91
	v_fma_f32 v88, -v52, v8, v88
	v_fma_f32 v89, -v53, v8, v89
	v_fma_f32 v90, -v54, v8, v90
	v_fma_f32 v91, -v55, v8, v91
	v_mul_f32_e32 v88, v86, v88
	v_mul_f32_e32 v89, v86, v89
	v_mul_f32_e32 v90, v86, v90
	v_mul_f32_e32 v91, v86, v91
	s_waitcnt vmcnt(0)
	v_mul_f32_e32 v2, v2, v88
	v_mul_f32_e32 v3, v3, v89
	v_mul_f32_e32 v4, v4, v90
	v_mul_f32_e32 v5, v5, v91
	v_cvt_pk_bf16_f32 v2, v2, v3
	v_cvt_pk_bf16_f32 v3, v4, v5
	global_store_dwordx2 v[150:151], v[2:3], off offset:80 sc1
	global_load_dwordx4 v[2:5], v1, s[0:1] offset:192
	s_waitcnt lgkmcnt(1)
	v_lshlrev_b32_e32 v88, 16, v92
	v_and_b32_e32 v89, 0xffff0000, v92
	v_lshlrev_b32_e32 v90, 16, v93
	v_and_b32_e32 v91, 0xffff0000, v93
	v_fma_f32 v88, -v56, v8, v88
	v_fma_f32 v89, -v57, v8, v89
	v_fma_f32 v90, -v58, v8, v90
	v_fma_f32 v91, -v59, v8, v91
	v_mul_f32_e32 v88, v86, v88
	v_mul_f32_e32 v89, v86, v89
	v_mul_f32_e32 v90, v86, v90
	v_mul_f32_e32 v91, v86, v91
	s_waitcnt vmcnt(0)
	v_mul_f32_e32 v2, v2, v88
	v_mul_f32_e32 v3, v3, v89
	v_mul_f32_e32 v4, v4, v90
	v_mul_f32_e32 v5, v5, v91
	v_cvt_pk_bf16_f32 v2, v2, v3
	v_cvt_pk_bf16_f32 v3, v4, v5
	global_store_dwordx2 v[150:151], v[2:3], off offset:96 sc1
	global_load_dwordx4 v[2:5], v1, s[0:1] offset:224
	s_waitcnt lgkmcnt(0)
	v_lshlrev_b32_e32 v88, 16, v94
	v_and_b32_e32 v89, 0xffff0000, v94
	v_lshlrev_b32_e32 v90, 16, v95
	v_and_b32_e32 v91, 0xffff0000, v95
	v_fma_f32 v88, -v60, v8, v88
	v_fma_f32 v89, -v61, v8, v89
	v_fma_f32 v90, -v62, v8, v90
	v_fma_f32 v91, -v63, v8, v91
	v_mul_f32_e32 v88, v86, v88
	v_mul_f32_e32 v89, v86, v89
	v_mul_f32_e32 v90, v86, v90
	v_mul_f32_e32 v91, v86, v91
	s_waitcnt vmcnt(0)
	v_mul_f32_e32 v2, v2, v88
	v_mul_f32_e32 v3, v3, v89
	v_mul_f32_e32 v4, v4, v90
	v_mul_f32_e32 v5, v5, v91
	v_cvt_pk_bf16_f32 v2, v2, v3
	v_cvt_pk_bf16_f32 v3, v4, v5
	global_store_dwordx2 v[150:151], v[2:3], off offset:112 sc1
	global_load_dwordx4 v[2:5], v1, s[0:1] offset:256
	ds_read2st64_b32 v[88:89], v139 offset0:124 offset1:125
	ds_read2st64_b32 v[90:91], v139 offset0:126 offset1:127
	ds_read2st64_b32 v[92:93], v139 offset0:128 offset1:129
	ds_read2st64_b32 v[94:95], v139 offset0:130 offset1:131
	s_waitcnt lgkmcnt(3)
	v_lshlrev_b32_e32 v96, 16, v88
	v_and_b32_e32 v97, 0xffff0000, v88
	v_lshlrev_b32_e32 v88, 16, v89
	v_and_b32_e32 v89, 0xffff0000, v89
	v_fma_f32 v96, -v32, v8, v96
	v_fma_f32 v97, -v33, v8, v97
	v_fma_f32 v88, -v34, v8, v88
	v_fma_f32 v89, -v35, v8, v89
	v_mul_f32_e32 v96, v86, v96
	v_mul_f32_e32 v97, v86, v97
	v_mul_f32_e32 v88, v86, v88
	v_mul_f32_e32 v89, v86, v89
	s_waitcnt vmcnt(0)
	v_mul_f32_e32 v2, v2, v96
	v_mul_f32_e32 v3, v3, v97
	v_mul_f32_e32 v4, v4, v88
	v_mul_f32_e32 v5, v5, v89
	v_cvt_pk_bf16_f32 v2, v2, v3
	v_cvt_pk_bf16_f32 v3, v4, v5
	global_store_dwordx2 v[150:151], v[2:3], off offset:128 sc1
	global_load_dwordx4 v[2:5], v1, s[0:1] offset:288
	s_waitcnt lgkmcnt(2)
	v_lshlrev_b32_e32 v88, 16, v90
	v_and_b32_e32 v89, 0xffff0000, v90
	v_lshlrev_b32_e32 v90, 16, v91
	v_and_b32_e32 v91, 0xffff0000, v91
	v_fma_f32 v88, -v36, v8, v88
	v_fma_f32 v89, -v37, v8, v89
	v_fma_f32 v90, -v38, v8, v90
	v_fma_f32 v91, -v39, v8, v91
	v_mul_f32_e32 v88, v86, v88
	v_mul_f32_e32 v89, v86, v89
	v_mul_f32_e32 v90, v86, v90
	v_mul_f32_e32 v91, v86, v91
	s_waitcnt vmcnt(0)
	v_mul_f32_e32 v2, v2, v88
	v_mul_f32_e32 v3, v3, v89
	v_mul_f32_e32 v4, v4, v90
	v_mul_f32_e32 v5, v5, v91
	v_cvt_pk_bf16_f32 v2, v2, v3
	v_cvt_pk_bf16_f32 v3, v4, v5
	global_store_dwordx2 v[150:151], v[2:3], off offset:144 sc1
	global_load_dwordx4 v[2:5], v1, s[0:1] offset:320
	s_waitcnt lgkmcnt(1)
	v_lshlrev_b32_e32 v88, 16, v92
	v_and_b32_e32 v89, 0xffff0000, v92
	v_lshlrev_b32_e32 v90, 16, v93
	v_and_b32_e32 v91, 0xffff0000, v93
	v_fma_f32 v88, -v40, v8, v88
	v_fma_f32 v89, -v41, v8, v89
	v_fma_f32 v90, -v42, v8, v90
	v_fma_f32 v91, -v43, v8, v91
	v_mul_f32_e32 v88, v86, v88
	v_mul_f32_e32 v89, v86, v89
	v_mul_f32_e32 v90, v86, v90
	v_mul_f32_e32 v91, v86, v91
	s_waitcnt vmcnt(0)
	v_mul_f32_e32 v2, v2, v88
	v_mul_f32_e32 v3, v3, v89
	v_mul_f32_e32 v4, v4, v90
	v_mul_f32_e32 v5, v5, v91
	v_cvt_pk_bf16_f32 v2, v2, v3
	v_cvt_pk_bf16_f32 v3, v4, v5
	global_store_dwordx2 v[150:151], v[2:3], off offset:160 sc1
	global_load_dwordx4 v[2:5], v1, s[0:1] offset:352
	s_waitcnt lgkmcnt(0)
	v_lshlrev_b32_e32 v88, 16, v94
	v_and_b32_e32 v89, 0xffff0000, v94
	v_lshlrev_b32_e32 v90, 16, v95
	v_and_b32_e32 v91, 0xffff0000, v95
	v_fma_f32 v88, -v44, v8, v88
	v_fma_f32 v89, -v45, v8, v89
	v_fma_f32 v90, -v46, v8, v90
	v_fma_f32 v91, -v47, v8, v91
	v_mul_f32_e32 v88, v86, v88
	v_mul_f32_e32 v89, v86, v89
	v_mul_f32_e32 v90, v86, v90
	v_mul_f32_e32 v91, v86, v91
	s_waitcnt vmcnt(0)
	v_mul_f32_e32 v2, v2, v88
	v_mul_f32_e32 v3, v3, v89
	v_mul_f32_e32 v4, v4, v90
	v_mul_f32_e32 v5, v5, v91
	v_cvt_pk_bf16_f32 v2, v2, v3
	v_cvt_pk_bf16_f32 v3, v4, v5
	global_store_dwordx2 v[150:151], v[2:3], off offset:176 sc1
	global_load_dwordx4 v[2:5], v1, s[0:1] offset:384
	ds_read2st64_b32 v[88:89], v139 offset0:132 offset1:133
	ds_read2st64_b32 v[90:91], v139 offset0:134 offset1:135
	ds_read2st64_b32 v[92:93], v139 offset0:136 offset1:137
	ds_read2st64_b32 v[94:95], v139 offset0:138 offset1:139
	s_waitcnt lgkmcnt(3)
	v_lshlrev_b32_e32 v96, 16, v88
	v_and_b32_e32 v97, 0xffff0000, v88
	v_lshlrev_b32_e32 v88, 16, v89
	v_and_b32_e32 v89, 0xffff0000, v89
	v_fma_f32 v96, -v16, v8, v96
	v_fma_f32 v97, -v17, v8, v97
	v_fma_f32 v9, -v19, v8, v89
	v_fma_f32 v8, -v18, v8, v88
	v_mul_f32_e32 v88, v86, v96
	v_mul_f32_e32 v89, v86, v97
	v_mul_f32_e32 v8, v86, v8
	v_mul_f32_e32 v9, v86, v9
	s_waitcnt vmcnt(0)
	v_mul_f32_e32 v2, v2, v88
	v_mul_f32_e32 v3, v3, v89
	v_mul_f32_e32 v4, v4, v8
	v_mul_f32_e32 v5, v5, v9
	v_cvt_pk_bf16_f32 v2, v2, v3
	v_cvt_pk_bf16_f32 v3, v4, v5
	global_store_dwordx2 v[150:151], v[2:3], off offset:192 sc1
	global_load_dwordx4 v[2:5], v1, s[0:1] offset:416
	v_mov_b32_e32 v8, v82
	v_mov_b32_e32 v9, v84
	v_mov_b32_e32 v84, v83
	s_waitcnt lgkmcnt(2)
	v_lshlrev_b32_e32 v82, 16, v90
	v_and_b32_e32 v83, 0xffff0000, v90
	v_lshlrev_b32_e32 v88, 16, v91
	v_and_b32_e32 v89, 0xffff0000, v91
	v_add_f32_e64 v8, v82, -v8
	v_add_f32_e64 v9, v83, -v9
	v_add_f32_e64 v82, v88, -v84
	v_add_f32_e64 v83, v89, -v85
	v_mul_f32_e32 v8, v86, v8
	v_mul_f32_e32 v9, v86, v9
	v_mul_f32_e32 v82, v86, v82
	v_mul_f32_e32 v83, v86, v83
	s_waitcnt vmcnt(0)
	v_mul_f32_e32 v2, v2, v8
	v_mul_f32_e32 v3, v3, v9
	v_mul_f32_e32 v4, v4, v82
	v_mul_f32_e32 v5, v5, v83
	v_cvt_pk_bf16_f32 v2, v2, v3
	v_cvt_pk_bf16_f32 v3, v4, v5
	global_store_dwordx2 v[150:151], v[2:3], off offset:208 sc1
	global_load_dwordx4 v[2:5], v1, s[0:1] offset:448
	v_mov_b32_e32 v8, v14
	v_mov_b32_e32 v9, v80
	v_mov_b32_e32 v80, v15
	s_waitcnt lgkmcnt(1)
	v_lshlrev_b32_e32 v14, 16, v92
	v_and_b32_e32 v15, 0xffff0000, v92
	v_lshlrev_b32_e32 v82, 16, v93
	v_and_b32_e32 v83, 0xffff0000, v93
	v_add_f32_e64 v8, v14, -v8
	v_add_f32_e64 v9, v15, -v9
	v_add_f32_e64 v14, v82, -v80
	v_add_f32_e64 v15, v83, -v81
	v_mul_f32_e32 v8, v86, v8
	v_mul_f32_e32 v9, v86, v9
	v_mul_f32_e32 v14, v86, v14
	v_mul_f32_e32 v15, v86, v15
	s_waitcnt vmcnt(0)
	v_mul_f32_e32 v2, v2, v8
	v_mul_f32_e32 v3, v3, v9
	v_mul_f32_e32 v4, v4, v14
	v_mul_f32_e32 v5, v5, v15
	v_cvt_pk_bf16_f32 v2, v2, v3
	v_cvt_pk_bf16_f32 v3, v4, v5
	global_store_dwordx2 v[150:151], v[2:3], off offset:224 sc1
	global_load_dwordx4 v[2:5], v1, s[0:1] offset:480
	v_mov_b32_e32 v8, v10
	v_mov_b32_e32 v9, v12
	v_mov_b32_e32 v12, v11
	s_waitcnt lgkmcnt(0)
	v_lshlrev_b32_e32 v10, 16, v94
	v_and_b32_e32 v11, 0xffff0000, v94
	v_lshlrev_b32_e32 v14, 16, v95
	v_and_b32_e32 v15, 0xffff0000, v95
	v_add_f32_e64 v8, v10, -v8
	v_add_f32_e64 v9, v11, -v9
	v_add_f32_e64 v10, v14, -v12
	v_add_f32_e64 v11, v15, -v13
	v_mul_f32_e32 v8, v86, v8
	v_mul_f32_e32 v9, v86, v9
	v_mul_f32_e32 v10, v86, v10
	v_mul_f32_e32 v11, v86, v11
	s_waitcnt vmcnt(0)
	v_mul_f32_e32 v2, v2, v8
	v_mul_f32_e32 v3, v3, v9
	v_mul_f32_e32 v4, v4, v10
	v_mul_f32_e32 v5, v5, v11
	v_cvt_pk_bf16_f32 v2, v2, v3
	v_cvt_pk_bf16_f32 v3, v4, v5
	global_store_dwordx2 v[150:151], v[2:3], off offset:240 sc1
	s_cbranch_execnz .LBB0_1016
	s_branch .LBB0_1029

.LBB0_1029:
	v_mul_f32_e32 v2, v64, v6
	v_mul_f32_e32 v3, v65, v6
	s_nop 0
	v_cvt_pk_bf16_f32 v1, v2, v3
	v_mul_f32_e32 v2, v66, v6
	v_mul_f32_e32 v3, v67, v6
	s_nop 0
	v_cvt_pk_bf16_f32 v2, v2, v3
	ds_write2st64_b32 v139, v1, v2 offset0:108 offset1:109
	v_mul_f32_e32 v2, v68, v6
	v_mul_f32_e32 v3, v69, v6
	s_nop 0
	v_cvt_pk_bf16_f32 v1, v2, v3
	v_mul_f32_e32 v2, v70, v6
	v_mul_f32_e32 v3, v71, v6
	s_nop 0
	v_cvt_pk_bf16_f32 v2, v2, v3
	ds_write2st64_b32 v139, v1, v2 offset0:110 offset1:111
	v_mul_f32_e32 v2, v72, v6
	v_mul_f32_e32 v3, v73, v6
	s_nop 0
	v_cvt_pk_bf16_f32 v1, v2, v3
	v_mul_f32_e32 v2, v74, v6
	v_mul_f32_e32 v3, v75, v6
	s_nop 0
	v_cvt_pk_bf16_f32 v2, v2, v3
	ds_write2st64_b32 v139, v1, v2 offset0:112 offset1:113
	v_mul_f32_e32 v2, v76, v6
	v_mul_f32_e32 v3, v77, v6
	s_nop 0
	v_cvt_pk_bf16_f32 v1, v2, v3
	v_mul_f32_e32 v2, v78, v6
	v_mul_f32_e32 v3, v79, v6
	s_nop 0
	v_cvt_pk_bf16_f32 v2, v2, v3
	ds_write2st64_b32 v139, v1, v2 offset0:114 offset1:115
	v_mul_f32_e32 v2, v48, v6
	v_mul_f32_e32 v3, v49, v6
	s_nop 0
	v_cvt_pk_bf16_f32 v1, v2, v3
	v_mul_f32_e32 v2, v50, v6
	v_mul_f32_e32 v3, v51, v6
	s_nop 0
	v_cvt_pk_bf16_f32 v2, v2, v3
	ds_write2st64_b32 v139, v1, v2 offset0:116 offset1:117
	v_mul_f32_e32 v2, v52, v6
	v_mul_f32_e32 v3, v53, v6
	s_nop 0
	v_cvt_pk_bf16_f32 v1, v2, v3
	v_mul_f32_e32 v2, v54, v6
	v_mul_f32_e32 v3, v55, v6
	s_nop 0
	v_cvt_pk_bf16_f32 v2, v2, v3
	ds_write2st64_b32 v139, v1, v2 offset0:118 offset1:119
	v_mul_f32_e32 v2, v56, v6
	v_mul_f32_e32 v3, v57, v6
	s_nop 0
	v_cvt_pk_bf16_f32 v1, v2, v3
	v_mul_f32_e32 v2, v58, v6
	v_mul_f32_e32 v3, v59, v6
	s_nop 0
	v_cvt_pk_bf16_f32 v2, v2, v3
	ds_write2st64_b32 v139, v1, v2 offset0:120 offset1:121
	v_mul_f32_e32 v2, v60, v6
	v_mul_f32_e32 v3, v61, v6
	s_nop 0
	v_cvt_pk_bf16_f32 v1, v2, v3
	v_mul_f32_e32 v2, v62, v6
	v_mul_f32_e32 v3, v63, v6
	s_nop 0
	v_cvt_pk_bf16_f32 v2, v2, v3
	ds_write2st64_b32 v139, v1, v2 offset0:122 offset1:123
	v_mul_f32_e32 v2, v32, v6
	v_mul_f32_e32 v3, v33, v6
	s_nop 0
	v_cvt_pk_bf16_f32 v1, v2, v3
	v_mul_f32_e32 v2, v34, v6
	v_mul_f32_e32 v3, v35, v6
	s_nop 0
	v_cvt_pk_bf16_f32 v2, v2, v3
	ds_write2st64_b32 v139, v1, v2 offset0:124 offset1:125
	v_mul_f32_e32 v2, v36, v6
	v_mul_f32_e32 v3, v37, v6
	s_nop 0
	v_cvt_pk_bf16_f32 v1, v2, v3
	v_mul_f32_e32 v2, v38, v6
	v_mul_f32_e32 v3, v39, v6
	s_nop 0
	v_cvt_pk_bf16_f32 v2, v2, v3
	ds_write2st64_b32 v139, v1, v2 offset0:126 offset1:127
	v_mul_f32_e32 v2, v40, v6
	v_mul_f32_e32 v3, v41, v6
	s_nop 0
	v_cvt_pk_bf16_f32 v1, v2, v3
	v_mul_f32_e32 v2, v42, v6
	v_mul_f32_e32 v3, v43, v6
	s_nop 0
	v_cvt_pk_bf16_f32 v2, v2, v3
	ds_write2st64_b32 v139, v1, v2 offset0:128 offset1:129
	v_mul_f32_e32 v2, v44, v6
	v_mul_f32_e32 v3, v45, v6
	s_nop 0
	v_cvt_pk_bf16_f32 v1, v2, v3
	v_mul_f32_e32 v2, v46, v6
	v_mul_f32_e32 v3, v47, v6
	s_nop 0
	v_cvt_pk_bf16_f32 v2, v2, v3
	ds_write2st64_b32 v139, v1, v2 offset0:130 offset1:131
	v_mul_f32_e32 v2, v16, v6
	v_mul_f32_e32 v3, v17, v6
	s_nop 0
	v_cvt_pk_bf16_f32 v1, v2, v3
	v_mul_f32_e32 v2, v18, v6
	v_mul_f32_e32 v3, v19, v6
	s_nop 0
	v_cvt_pk_bf16_f32 v2, v2, v3
	ds_write2st64_b32 v139, v1, v2 offset0:132 offset1:133
	v_mul_f32_e32 v2, v20, v6
	v_mul_f32_e32 v3, v21, v6
	s_nop 0
	v_cvt_pk_bf16_f32 v1, v2, v3
	v_mul_f32_e32 v2, v22, v6
	v_mul_f32_e32 v3, v23, v6
	s_nop 0
	v_cvt_pk_bf16_f32 v2, v2, v3
	ds_write2st64_b32 v139, v1, v2 offset0:134 offset1:135
	v_mul_f32_e32 v2, v24, v6
	v_mul_f32_e32 v3, v25, v6
	s_nop 0
	v_cvt_pk_bf16_f32 v1, v2, v3
	v_mul_f32_e32 v2, v26, v6
	v_mul_f32_e32 v3, v27, v6
	s_nop 0
	v_cvt_pk_bf16_f32 v2, v2, v3
	ds_write2st64_b32 v139, v1, v2 offset0:136 offset1:137
	v_mul_f32_e32 v2, v28, v6
	v_mul_f32_e32 v3, v29, v6
	s_nop 0
	v_cvt_pk_bf16_f32 v1, v2, v3
	v_mul_f32_e32 v2, v30, v6
	v_mul_f32_e32 v3, v31, v6
	ds_write_b32 v139, v1 offset:35328
	v_cvt_pk_bf16_f32 v1, v2, v3
	ds_write_b32 v195, v1 offset:27648
	s_branch .LBB0_1016

.LBB0_1285:
	v_fma_f32 v64, v64, s18, -v152
	v_fma_f32 v65, v65, s18, -v153
	v_fma_f32 v72, v72, s18, -v152
	v_fma_f32 v73, v73, s18, -v153
	v_exp_f32_e32 v98, v64
	v_exp_f32_e32 v99, v65
	v_fma_f32 v64, v66, s18, -v152
	v_fma_f32 v65, v67, s18, -v153
	ds_read_b128 v[82:85], v171 offset:17504
	v_exp_f32_e32 v100, v64
	v_exp_f32_e32 v101, v65
	v_fma_f32 v64, v68, s18, -v152
	v_fma_f32 v65, v69, s18, -v153
	v_fma_f32 v68, v70, s18, -v152
	v_fma_f32 v69, v71, s18, -v153
	v_exp_f32_e32 v102, v64
	v_exp_f32_e32 v103, v65
	ds_read_b128 v[64:67], v171 offset:17472
	v_exp_f32_e32 v104, v68
	v_exp_f32_e32 v105, v69
	v_cvt_pk_bf16_f32 v68, v98, v99
	v_cvt_pk_bf16_f32 v69, v100, v101
	v_cvt_pk_bf16_f32 v70, v102, v103
	v_cvt_pk_bf16_f32 v71, v104, v105
	v_exp_f32_e32 v72, v72
	v_exp_f32_e32 v73, v73
	s_waitcnt lgkmcnt(0)
	v_mfma_f32_32x32x16_bf16 v[48:63], v[64:67], v[68:71], v[48:63]
	ds_read_b128 v[64:67], v171 offset:22080
	ds_read_b128 v[86:89], v171 offset:22112
	s_lshl_b32 s8, s24, 1
	s_add_i32 s41, s41, s33
	s_cmpk_gt_i32 s41, 0x3ff
	s_waitcnt lgkmcnt(1)
	v_mfma_f32_32x32x16_bf16 v[32:47], v[64:67], v[68:71], v[32:47]
	ds_read_b128 v[64:67], v171 offset:26688
	ds_read_b128 v[90:93], v171 offset:31296
	ds_read_b128 v[94:97], v171 offset:26720
	s_waitcnt lgkmcnt(2)
	v_mfma_f32_32x32x16_bf16 v[16:31], v[64:67], v[68:71], v[16:31]
	v_fma_f32 v64, v74, s18, -v152
	v_fma_f32 v65, v75, s18, -v153
	v_exp_f32_e32 v74, v64
	v_exp_f32_e32 v75, v65
	v_fma_f32 v64, v76, s18, -v152
	v_fma_f32 v65, v77, s18, -v153
	s_nop 0
	v_exp_f32_e32 v76, v64
	s_waitcnt lgkmcnt(1)
	v_mfma_f32_32x32x16_bf16 v[0:15], v[90:93], v[68:71], v[0:15]
	v_fma_f32 v68, v78, s18, -v152
	v_fma_f32 v69, v79, s18, -v153
	v_exp_f32_e32 v77, v65
	v_exp_f32_e32 v78, v68
	v_exp_f32_e32 v79, v69
	v_cvt_pk_bf16_f32 v68, v72, v73
	v_cvt_pk_bf16_f32 v69, v74, v75
	v_cvt_pk_bf16_f32 v70, v76, v77
	v_cvt_pk_bf16_f32 v71, v78, v79
	ds_read_b128 v[64:67], v171 offset:31328
	s_nop 0
	v_mfma_f32_32x32x16_bf16 v[48:63], v[82:85], v[68:71], v[48:63]
	v_add_f32_e64 v82, v98, 0
	v_add_f32_e64 v83, v99, 0
	v_add_f32_e64 v82, v100, v82
	v_add_f32_e64 v83, v101, v83
	v_add_f32_e64 v82, v102, v82
	v_add_f32_e64 v83, v103, v83
	v_add_f32_e32 v82, v104, v82
	v_add_f32_e32 v83, v105, v83
	v_mfma_f32_32x32x16_bf16 v[32:47], v[86:89], v[68:71], v[32:47]
	v_add_f32_e64 v72, v72, v82
	v_add_f32_e64 v73, v73, v83
	v_add_f32_e64 v72, v74, v72
	v_add_f32_e64 v73, v75, v73
	v_add_f32_e64 v72, v76, v72
	v_add_f32_e64 v73, v77, v73
	v_add_f32_e32 v72, v78, v72
	v_add_f32_e32 v73, v79, v73
	s_waitcnt lgkmcnt(1)
	v_mfma_f32_32x32x16_bf16 v[16:31], v[94:97], v[68:71], v[16:31]
	v_add_f32_e32 v72, v72, v73
	v_add_f32_e32 v74, v80, v72
	ds_bpermute_b32 v75, v168, v74
	v_lshl_add_u64 v[72:73], s[6:7], 0, v[150:151]
	v_lshl_add_u64 v[72:73], v[72:73], 0, s[8:9]
	s_waitcnt lgkmcnt(0)
	v_add_f32_e32 v74, v74, v75
	v_div_scale_f32 v75, s[26:27], v74, v74, 1.0
	v_rcp_f32_e32 v76, v75
	v_mfma_f32_32x32x16_bf16 v[0:15], v[64:67], v[68:71], v[0:15]
	v_fma_f32 v64, -v75, v76, 1.0
	v_fmac_f32_e32 v76, v64, v76
	v_div_scale_f32 v64, vcc, 1.0, v74, 1.0
	v_mul_f32_e32 v65, v64, v76
	v_fma_f32 v66, -v75, v65, v64
	v_fmac_f32_e32 v65, v66, v76
	v_fma_f32 v64, -v75, v65, v64
	v_div_fmas_f32 v64, v64, v76, v65
	v_div_fixup_f32 v64, v64, v74, 1.0
	v_mul_f32_e32 v48, v48, v64
	v_mul_f32_e32 v49, v49, v64
	v_mul_f32_e32 v50, v50, v64
	v_mul_f32_e32 v51, v51, v64
	v_mul_f32_e32 v32, v32, v64
	v_mul_f32_e32 v33, v33, v64
	v_mul_f32_e32 v34, v34, v64
	v_mul_f32_e32 v35, v35, v64
	v_mul_f32_e32 v16, v16, v64
	v_mul_f32_e32 v17, v17, v64
	v_mul_f32_e32 v18, v18, v64
	v_mul_f32_e32 v19, v19, v64
	v_mul_f32_e32 v0, v0, v64
	v_mul_f32_e32 v1, v1, v64
	v_mul_f32_e32 v2, v2, v64
	v_mul_f32_e32 v3, v3, v64
	v_mul_f32_e32 v52, v52, v64
	v_mul_f32_e32 v53, v53, v64
	v_mul_f32_e32 v54, v54, v64
	v_mul_f32_e32 v55, v55, v64
	v_mul_f32_e32 v56, v56, v64
	v_mul_f32_e32 v57, v57, v64
	v_mul_f32_e32 v58, v58, v64
	v_mul_f32_e32 v59, v59, v64
	v_mul_f32_e32 v60, v60, v64
	v_mul_f32_e32 v61, v61, v64
	v_mul_f32_e32 v62, v62, v64
	v_mul_f32_e32 v63, v63, v64
	v_mul_f32_e32 v36, v36, v64
	v_mul_f32_e32 v37, v37, v64
	v_mul_f32_e32 v38, v38, v64
	v_mul_f32_e32 v39, v39, v64
	v_mul_f32_e32 v40, v40, v64
	v_mul_f32_e32 v41, v41, v64
	v_mul_f32_e32 v42, v42, v64
	v_mul_f32_e32 v43, v43, v64
	v_mul_f32_e32 v44, v44, v64
	v_mul_f32_e32 v45, v45, v64
	v_mul_f32_e32 v46, v46, v64
	v_mul_f32_e32 v47, v47, v64
	v_mul_f32_e32 v20, v20, v64
	v_mul_f32_e32 v21, v21, v64
	v_mul_f32_e32 v22, v22, v64
	v_mul_f32_e32 v23, v23, v64
	v_mul_f32_e32 v24, v24, v64
	v_mul_f32_e32 v25, v25, v64
	v_mul_f32_e32 v26, v26, v64
	v_mul_f32_e32 v27, v27, v64
	v_mul_f32_e32 v28, v28, v64
	v_mul_f32_e32 v29, v29, v64
	v_mul_f32_e32 v30, v30, v64
	v_mul_f32_e32 v31, v31, v64
	v_mul_f32_e32 v4, v4, v64
	v_mul_f32_e32 v5, v5, v64
	v_mul_f32_e32 v6, v6, v64
	v_mul_f32_e32 v7, v7, v64
	v_mul_f32_e32 v8, v8, v64
	v_mul_f32_e32 v9, v9, v64
	v_mul_f32_e32 v10, v10, v64
	v_mul_f32_e32 v11, v11, v64
	v_mul_f32_e32 v12, v12, v64
	v_mul_f32_e32 v13, v13, v64
	v_mul_f32_e32 v14, v14, v64
	v_mul_f32_e32 v15, v15, v64
	v_lshl_add_u64 v[64:65], v[72:73], 0, v[144:145]
	v_cvt_pk_bf16_f32 v48, v48, v49
	v_cvt_pk_bf16_f32 v49, v50, v51
	v_cvt_pk_bf16_f32 v32, v32, v33
	v_cvt_pk_bf16_f32 v33, v34, v35
	v_cvt_pk_bf16_f32 v16, v16, v17
	v_cvt_pk_bf16_f32 v17, v18, v19
	v_cvt_pk_bf16_f32 v0, v0, v1
	v_cvt_pk_bf16_f32 v1, v2, v3
	global_store_dwordx2 v[64:65], v[48:49], off sc1
	v_cvt_pk_bf16_f32 v48, v52, v53
	v_cvt_pk_bf16_f32 v49, v54, v55
	global_store_dwordx2 v[64:65], v[32:33], off offset:64 sc1
	v_cvt_pk_bf16_f32 v32, v36, v37
	v_cvt_pk_bf16_f32 v33, v38, v39
	global_store_dwordx2 v[64:65], v[16:17], off offset:128 sc1
	v_cvt_pk_bf16_f32 v16, v20, v21
	v_cvt_pk_bf16_f32 v17, v22, v23
	global_store_dwordx2 v[64:65], v[0:1], off offset:192 sc1
	v_cvt_pk_bf16_f32 v0, v4, v5
	v_cvt_pk_bf16_f32 v1, v6, v7
	global_store_dwordx2 v[64:65], v[48:49], off offset:16 sc1
	v_cvt_pk_bf16_f32 v48, v56, v57
	v_cvt_pk_bf16_f32 v49, v58, v59
	global_store_dwordx2 v[64:65], v[32:33], off offset:80 sc1
	v_cvt_pk_bf16_f32 v32, v40, v41
	v_cvt_pk_bf16_f32 v33, v42, v43
	global_store_dwordx2 v[64:65], v[16:17], off offset:144 sc1
	v_cvt_pk_bf16_f32 v16, v24, v25
	v_cvt_pk_bf16_f32 v17, v26, v27
	global_store_dwordx2 v[64:65], v[0:1], off offset:208 sc1
	v_cvt_pk_bf16_f32 v0, v8, v9
	v_cvt_pk_bf16_f32 v1, v10, v11
	global_store_dwordx2 v[64:65], v[48:49], off offset:32 sc1
	v_cvt_pk_bf16_f32 v48, v60, v61
	v_cvt_pk_bf16_f32 v49, v62, v63
	global_store_dwordx2 v[64:65], v[32:33], off offset:96 sc1
	v_cvt_pk_bf16_f32 v32, v44, v45
	v_cvt_pk_bf16_f32 v33, v46, v47
	global_store_dwordx2 v[64:65], v[16:17], off offset:160 sc1
	v_cvt_pk_bf16_f32 v16, v28, v29
	v_cvt_pk_bf16_f32 v17, v30, v31
	global_store_dwordx2 v[64:65], v[0:1], off offset:224 sc1
	v_cvt_pk_bf16_f32 v0, v12, v13
	v_cvt_pk_bf16_f32 v1, v14, v15
	global_store_dwordx2 v[64:65], v[48:49], off offset:48 sc1
	global_store_dwordx2 v[64:65], v[32:33], off offset:112 sc1
	global_store_dwordx2 v[64:65], v[16:17], off offset:176 sc1
	global_store_dwordx2 v[64:65], v[0:1], off offset:240 sc1
	s_cbranch_scc1 .LBB0_1306

.LBB0_1295:
	v_max_f32_e32 v152, v152, v152
	v_max_f32_e32 v173, v153, v153
	v_max_f32_e32 v152, v173, v152
	v_sub_f32_e32 v153, v153, v152
	v_exp_f32_e32 v174, v153
	v_mov_b32_e32 v153, v152
	v_mul_f32_e32 v62, v62, v174
	v_mul_f32_e32 v63, v63, v174
	v_mul_f32_e32 v60, v60, v174
	v_mul_f32_e32 v61, v61, v174
	v_mul_f32_e32 v58, v58, v174
	v_mul_f32_e32 v59, v59, v174
	v_mul_f32_e32 v56, v56, v174
	v_mul_f32_e32 v57, v57, v174
	v_mul_f32_e32 v54, v54, v174
	v_mul_f32_e32 v55, v55, v174
	v_mul_f32_e32 v52, v52, v174
	v_mul_f32_e32 v53, v53, v174
	v_mul_f32_e32 v50, v50, v174
	v_mul_f32_e32 v51, v51, v174
	v_mul_f32_e32 v48, v48, v174
	v_mul_f32_e32 v49, v49, v174
	v_mul_f32_e32 v46, v46, v174
	v_mul_f32_e32 v47, v47, v174
	v_mul_f32_e32 v44, v44, v174
	v_mul_f32_e32 v45, v45, v174
	v_mul_f32_e32 v42, v42, v174
	v_mul_f32_e32 v43, v43, v174
	v_mul_f32_e32 v40, v40, v174
	v_mul_f32_e32 v41, v41, v174
	v_mul_f32_e32 v38, v38, v174
	v_mul_f32_e32 v39, v39, v174
	v_mul_f32_e32 v36, v36, v174
	v_mul_f32_e32 v37, v37, v174
	v_mul_f32_e32 v34, v34, v174
	v_mul_f32_e32 v35, v35, v174
	v_mul_f32_e32 v32, v32, v174
	v_mul_f32_e32 v33, v33, v174
	v_mul_f32_e32 v30, v30, v174
	v_mul_f32_e32 v31, v31, v174
	v_mul_f32_e32 v28, v28, v174
	v_mul_f32_e32 v29, v29, v174
	v_mul_f32_e32 v26, v26, v174
	v_mul_f32_e32 v27, v27, v174
	v_mul_f32_e32 v24, v24, v174
	v_mul_f32_e32 v25, v25, v174
	v_mul_f32_e32 v22, v22, v174
	v_mul_f32_e32 v23, v23, v174
	v_mul_f32_e32 v20, v20, v174
	v_mul_f32_e32 v21, v21, v174
	v_mul_f32_e32 v18, v18, v174
	v_mul_f32_e32 v19, v19, v174
	v_mul_f32_e32 v16, v16, v174
	v_mul_f32_e32 v17, v17, v174
	v_mul_f32_e32 v14, v14, v174
	v_mul_f32_e32 v15, v15, v174
	v_mul_f32_e32 v12, v12, v174
	v_mul_f32_e32 v13, v13, v174
	v_mul_f32_e32 v10, v10, v174
	v_mul_f32_e32 v11, v11, v174
	v_mul_f32_e32 v8, v8, v174
	v_mul_f32_e32 v9, v9, v174
	v_mul_f32_e32 v6, v6, v174
	v_mul_f32_e32 v7, v7, v174
	v_mul_f32_e32 v4, v4, v174
	v_mul_f32_e32 v5, v5, v174
	v_mul_f32_e32 v2, v2, v174
	v_mul_f32_e32 v3, v3, v174
	v_mul_f32_e32 v0, v0, v174
	v_mul_f32_e32 v1, v1, v174
	v_mul_f32_e32 v172, v172, v174
.LBB0_1296:
	v_fma_f32 v64, v64, s18, -v152
	v_fma_f32 v65, v65, s18, -v153
	v_fma_f32 v72, v72, s18, -v152
	v_fma_f32 v73, v73, s18, -v153
	v_exp_f32_e32 v190, v64
	v_exp_f32_e32 v191, v65
	v_fma_f32 v64, v66, s18, -v152
	v_fma_f32 v65, v67, s18, -v153
	ds_read_b128 v[174:177], v171 offset:17504
	v_exp_f32_e32 v192, v64
	v_exp_f32_e32 v193, v65
	v_fma_f32 v64, v68, s18, -v152
	v_fma_f32 v65, v69, s18, -v153
	v_fma_f32 v68, v70, s18, -v152
	v_fma_f32 v69, v71, s18, -v153
	v_exp_f32_e32 v194, v64
	v_exp_f32_e32 v195, v65
	ds_read_b128 v[64:67], v171 offset:17472
	v_exp_f32_e32 v196, v68
	v_exp_f32_e32 v197, v69
	v_cvt_pk_bf16_f32 v68, v190, v191
	v_cvt_pk_bf16_f32 v69, v192, v193
	v_cvt_pk_bf16_f32 v70, v194, v195
	v_cvt_pk_bf16_f32 v71, v196, v197
	v_exp_f32_e32 v72, v72
	v_exp_f32_e32 v73, v73
	s_waitcnt lgkmcnt(0)
	v_mfma_f32_32x32x16_bf16 v[48:63], v[64:67], v[68:71], v[48:63]
	ds_read_b128 v[64:67], v171 offset:22080
	ds_read_b128 v[178:181], v171 offset:22112
	s_add_i32 s25, s25, -1
	v_lshl_add_u64 v[154:155], v[154:155], 0, s[20:21]
	v_lshl_add_u64 v[156:157], v[156:157], 0, s[20:21]
	v_lshl_add_u64 v[158:159], v[158:159], 0, s[20:21]
	v_lshl_add_u64 v[160:161], v[160:161], 0, s[20:21]
	s_cmp_eq_u32 s25, 0
	s_waitcnt lgkmcnt(1)
	v_mfma_f32_32x32x16_bf16 v[32:47], v[64:67], v[68:71], v[32:47]
	ds_read_b128 v[64:67], v171 offset:26688
	ds_read_b128 v[182:185], v171 offset:31296
	ds_read_b128 v[186:189], v171 offset:26720
	v_lshl_add_u64 v[162:163], v[162:163], 0, s[22:23]
	s_waitcnt lgkmcnt(2)
	v_mfma_f32_32x32x16_bf16 v[16:31], v[64:67], v[68:71], v[16:31]
	v_fma_f32 v64, v74, s18, -v152
	v_fma_f32 v65, v75, s18, -v153
	v_exp_f32_e32 v74, v64
	v_exp_f32_e32 v75, v65
	v_fma_f32 v64, v76, s18, -v152
	v_fma_f32 v65, v77, s18, -v153
	s_nop 0
	v_exp_f32_e32 v76, v64
	v_exp_f32_e32 v77, v65
	ds_read_b128 v[64:67], v171 offset:31328
	s_waitcnt lgkmcnt(2)
	v_mfma_f32_32x32x16_bf16 v[0:15], v[182:185], v[68:71], v[0:15]
	v_fma_f32 v68, v78, s18, -v152
	v_fma_f32 v69, v79, s18, -v153
	v_cvt_pk_bf16_f32 v70, v76, v77
	v_exp_f32_e32 v78, v68
	v_exp_f32_e32 v79, v69
	v_cvt_pk_bf16_f32 v68, v72, v73
	v_cvt_pk_bf16_f32 v69, v74, v75
	v_cvt_pk_bf16_f32 v71, v78, v79
	s_nop 1
	v_mfma_f32_32x32x16_bf16 v[48:63], v[174:177], v[68:71], v[48:63]
	v_add_f32_e64 v174, v190, 0
	v_add_f32_e64 v175, v191, 0
	v_add_f32_e64 v174, v192, v174
	v_add_f32_e64 v175, v193, v175
	v_add_f32_e64 v174, v194, v174
	v_add_f32_e64 v175, v195, v175
	v_add_f32_e32 v174, v196, v174
	v_add_f32_e32 v175, v197, v175
	v_mfma_f32_32x32x16_bf16 v[32:47], v[178:181], v[68:71], v[32:47]
	v_add_f32_e64 v72, v72, v174
	v_add_f32_e64 v73, v73, v175
	v_add_f32_e64 v72, v74, v72
	v_add_f32_e64 v73, v75, v73
	v_add_f32_e64 v72, v76, v72
	v_add_f32_e64 v73, v77, v73
	v_add_f32_e32 v72, v78, v72
	v_add_f32_e32 v73, v79, v73
	s_waitcnt lgkmcnt(1)
	v_mfma_f32_32x32x16_bf16 v[16:31], v[186:189], v[68:71], v[16:31]
	v_add_f32_e32 v72, v72, v73
	v_add_f32_e32 v172, v172, v72
	s_waitcnt lgkmcnt(0)
	v_mfma_f32_32x32x16_bf16 v[0:15], v[64:67], v[68:71], v[0:15]
	s_cbranch_scc1 .LBB0_1301
.LBB0_1297:
	s_barrier
	s_waitcnt vmcnt(3)
	ds_write_b128 v166, v[112:115]
	s_waitcnt vmcnt(2)
	ds_write_b128 v166, v[116:119] offset:4352
	s_waitcnt vmcnt(1)
	ds_write_b128 v166, v[120:123] offset:8704
	s_waitcnt vmcnt(0)
	ds_write_b128 v166, v[124:127] offset:13056
	s_waitcnt vmcnt(1)
	ds_write_b128 v167, v[140:143] offset:17408
	ds_write_b128 v167, v[132:135] offset:22016
	ds_write_b128 v167, v[128:131] offset:26624
	s_waitcnt vmcnt(0)
	ds_write_b128 v167, v[136:139] offset:31232
	s_waitcnt lgkmcnt(0)
	s_barrier
	ds_read_b128 v[64:67], v170
	ds_read_b128 v[112:115], v170 offset:32
	s_waitcnt lgkmcnt(1)
	v_mfma_f32_32x32x16_bf16 v[64:79], v[64:67], v[108:111], 0
	v_lshl_add_u64 v[124:125], s[14:15], 0, v[162:163]
	v_add_co_u32_e32 v178, vcc, s37, v124
	v_lshl_add_u64 v[126:127], s[14:15], 0, v[154:155]
	s_nop 0
	v_addc_co_u32_e32 v179, vcc, 0, v125, vcc
	v_add_co_u32_e32 v180, vcc, s38, v124
	s_waitcnt lgkmcnt(0)
	v_mfma_f32_32x32x16_bf16 v[64:79], v[112:115], v[104:107], v[64:79]
	ds_read_b128 v[112:115], v170 offset:64
	ds_read_b128 v[116:119], v170 offset:96
	v_lshl_add_u64 v[128:129], s[14:15], 0, v[156:157]
	v_lshl_add_u64 v[130:131], s[14:15], 0, v[158:159]
	v_lshl_add_u64 v[136:137], s[14:15], 0, v[160:161]
	v_addc_co_u32_e32 v181, vcc, 0, v125, vcc
	v_add_co_u32_e32 v182, vcc, s39, v124
	s_waitcnt lgkmcnt(1)
	v_mfma_f32_32x32x16_bf16 v[64:79], v[112:115], v[100:103], v[64:79]
	ds_read_b128 v[112:115], v170 offset:128
	v_addc_co_u32_e32 v183, vcc, 0, v125, vcc
	v_add_co_u32_e32 v124, vcc, s40, v124
	s_nop 1
	v_addc_co_u32_e32 v125, vcc, 0, v125, vcc
	s_waitcnt lgkmcnt(1)
	v_mfma_f32_32x32x16_bf16 v[64:79], v[116:119], v[96:99], v[64:79]
	ds_read_b128 v[116:119], v170 offset:160
	ds_read_b128 v[120:123], v170 offset:192
	ds_read_b128 v[174:177], v170 offset:224
	s_waitcnt lgkmcnt(3)
	v_mfma_f32_32x32x16_bf16 v[64:79], v[112:115], v[92:95], v[64:79]
	s_waitcnt lgkmcnt(2)
	v_mfma_f32_32x32x16_bf16 v[64:79], v[116:119], v[88:91], v[64:79]
	global_load_dwordx4 v[140:143], v[126:127], off
	global_load_dwordx4 v[132:135], v[128:129], off
	s_nop 0
	global_load_dwordx4 v[128:131], v[130:131], off
	s_nop 0
	global_load_dwordx4 v[136:139], v[136:137], off
	s_nop 0
	global_load_dwordx4 v[112:115], v[178:179], off
	global_load_dwordx4 v[116:119], v[180:181], off
	s_waitcnt lgkmcnt(1)
	v_mfma_f32_32x32x16_bf16 v[64:79], v[120:123], v[84:87], v[64:79]
	global_load_dwordx4 v[120:123], v[182:183], off
	s_nop 0
	global_load_dwordx4 v[124:127], v[124:125], off
	s_waitcnt lgkmcnt(0)
	v_mfma_f32_32x32x16_bf16 v[64:79], v[174:177], v[80:83], v[64:79]
	s_nop 11
	v_max_f32_e32 v152, v65, v65
	v_max_f32_e32 v173, v64, v64
	v_max_f32_e32 v152, v173, v152
	v_max3_f32 v152, v152, v66, v67
	v_max3_f32 v152, v152, v68, v69
	v_max3_f32 v152, v152, v70, v71
	v_max3_f32 v152, v152, v72, v73
	v_max3_f32 v152, v152, v74, v75
	v_max3_f32 v152, v152, v76, v77
	v_max3_f32 v152, v152, v78, v79
	ds_bpermute_b32 v173, v168, v152
	s_waitcnt lgkmcnt(0)
	v_max_f32_e32 v173, v173, v173
	v_max_f32_e32 v152, v152, v173
	v_mul_f32_e32 v152, 0x3e0293ee, v152
	v_cmp_gt_f32_e32 vcc, v152, v153
	s_cbranch_vccz .LBB0_1299
	v_max_f32_e32 v152, v152, v152
	v_max_f32_e32 v173, v153, v153
	v_max_f32_e32 v173, v173, v152
	v_sub_f32_e32 v152, v153, v173
	v_exp_f32_e32 v152, v152
	s_nop 0
	v_mul_f32_e32 v62, v62, v152
	v_mul_f32_e32 v63, v63, v152
	v_mul_f32_e32 v60, v60, v152
	v_mul_f32_e32 v61, v61, v152
	v_mul_f32_e32 v58, v58, v152
	v_mul_f32_e32 v59, v59, v152
	v_mul_f32_e32 v56, v56, v152
	v_mul_f32_e32 v57, v57, v152
	v_mul_f32_e32 v54, v54, v152
	v_mul_f32_e32 v55, v55, v152
	v_mul_f32_e32 v52, v52, v152
	v_mul_f32_e32 v53, v53, v152
	v_mul_f32_e32 v50, v50, v152
	v_mul_f32_e32 v51, v51, v152
	v_mul_f32_e32 v48, v48, v152
	v_mul_f32_e32 v49, v49, v152
	v_mul_f32_e32 v46, v46, v152
	v_mul_f32_e32 v47, v47, v152
	v_mul_f32_e32 v44, v44, v152
	v_mul_f32_e32 v45, v45, v152
	v_mul_f32_e32 v42, v42, v152
	v_mul_f32_e32 v43, v43, v152
	v_mul_f32_e32 v40, v40, v152
	v_mul_f32_e32 v41, v41, v152
	v_mul_f32_e32 v38, v38, v152
	v_mul_f32_e32 v39, v39, v152
	v_mul_f32_e32 v36, v36, v152
	v_mul_f32_e32 v37, v37, v152
	v_mul_f32_e32 v34, v34, v152
	v_mul_f32_e32 v35, v35, v152
	v_mul_f32_e32 v32, v32, v152
	v_mul_f32_e32 v33, v33, v152
	v_mul_f32_e32 v30, v30, v152
	v_mul_f32_e32 v31, v31, v152
	v_mul_f32_e32 v28, v28, v152
	v_mul_f32_e32 v29, v29, v152
	v_mul_f32_e32 v26, v26, v152
	v_mul_f32_e32 v27, v27, v152
	v_mul_f32_e32 v24, v24, v152
	v_mul_f32_e32 v25, v25, v152
	v_mul_f32_e32 v22, v22, v152
	v_mul_f32_e32 v23, v23, v152
	v_mul_f32_e32 v20, v20, v152
	v_mul_f32_e32 v21, v21, v152
	v_mul_f32_e32 v18, v18, v152
	v_mul_f32_e32 v19, v19, v152
	v_mul_f32_e32 v16, v16, v152
	v_mul_f32_e32 v17, v17, v152
	v_mul_f32_e32 v14, v14, v152
	v_mul_f32_e32 v15, v15, v152
	v_mul_f32_e32 v12, v12, v152
	v_mul_f32_e32 v13, v13, v152
	v_mul_f32_e32 v10, v10, v152
	v_mul_f32_e32 v11, v11, v152
	v_mul_f32_e32 v8, v8, v152
	v_mul_f32_e32 v9, v9, v152
	v_mul_f32_e32 v6, v6, v152
	v_mul_f32_e32 v7, v7, v152
	v_mul_f32_e32 v4, v4, v152
	v_mul_f32_e32 v5, v5, v152
	v_mul_f32_e32 v2, v2, v152
	v_mul_f32_e32 v3, v3, v152
	v_mul_f32_e32 v0, v0, v152
	v_mul_f32_e32 v1, v1, v152
	v_mul_f32_e32 v172, v172, v152
	v_mov_b32_e32 v153, v173
.LBB0_1299:
	v_mov_b32_e32 v152, v153
	v_fma_f32 v64, v64, s18, -v152
	v_fma_f32 v65, v65, s18, -v152
	v_fma_f32 v72, v72, s18, -v152
	v_fma_f32 v73, v73, s18, -v152
	v_exp_f32_e32 v202, v64
	v_exp_f32_e32 v203, v65
	v_fma_f32 v64, v66, s18, -v152
	v_fma_f32 v65, v67, s18, -v152
	ds_read_b128 v[174:177], v171 offset:17440
	v_exp_f32_e32 v204, v64
	v_exp_f32_e32 v205, v65
	v_fma_f32 v64, v68, s18, -v152
	v_fma_f32 v65, v69, s18, -v152
	v_fma_f32 v68, v70, s18, -v152
	v_fma_f32 v69, v71, s18, -v152
	v_exp_f32_e32 v206, v64
	v_exp_f32_e32 v207, v65
	ds_read_b128 v[64:67], v171 offset:17408
	v_exp_f32_e32 v208, v68
	v_exp_f32_e32 v209, v69
	v_cvt_pk_bf16_f32 v68, v202, v203
	v_cvt_pk_bf16_f32 v69, v204, v205
	v_cvt_pk_bf16_f32 v70, v206, v207
	v_cvt_pk_bf16_f32 v71, v208, v209
	v_exp_f32_e32 v210, v72
	v_exp_f32_e32 v211, v73
	s_waitcnt lgkmcnt(0)
	v_mfma_f32_32x32x16_bf16 v[48:63], v[64:67], v[68:71], v[48:63]
	ds_read_b128 v[64:67], v171 offset:22016
	ds_read_b128 v[178:181], v171 offset:22048
	s_waitcnt lgkmcnt(1)
	v_mfma_f32_32x32x16_bf16 v[32:47], v[64:67], v[68:71], v[32:47]
	ds_read_b128 v[64:67], v171 offset:26624
	ds_read_b128 v[182:185], v171 offset:31232
	ds_read_b128 v[186:189], v171 offset:26656
	ds_read_b128 v[190:193], v171 offset:31264
	s_waitcnt lgkmcnt(3)
	v_mfma_f32_32x32x16_bf16 v[16:31], v[64:67], v[68:71], v[16:31]
	v_fma_f32 v64, v74, s18, -v152
	v_fma_f32 v65, v75, s18, -v152
	v_exp_f32_e32 v212, v64
	v_exp_f32_e32 v213, v65
	v_fma_f32 v64, v76, s18, -v152
	v_fma_f32 v65, v77, s18, -v152
	s_nop 0
	v_exp_f32_e32 v214, v64
	v_exp_f32_e32 v215, v65
	v_fma_f32 v64, v78, s18, -v152
	v_fma_f32 v65, v79, s18, -v152
	s_waitcnt lgkmcnt(2)
	v_mfma_f32_32x32x16_bf16 v[0:15], v[182:185], v[68:71], v[0:15]
	v_exp_f32_e32 v216, v64
	v_exp_f32_e32 v217, v65
	v_cvt_pk_bf16_f32 v182, v210, v211
	v_cvt_pk_bf16_f32 v183, v212, v213
	v_cvt_pk_bf16_f32 v184, v214, v215
	v_cvt_pk_bf16_f32 v185, v216, v217
	s_nop 1
	v_mfma_f32_32x32x16_bf16 v[48:63], v[174:177], v[182:185], v[48:63]
	ds_read_b128 v[64:67], v170 offset:8704
	ds_read_b128 v[174:177], v170 offset:8736
	s_waitcnt lgkmcnt(1)
	v_mfma_f32_32x32x16_bf16 v[64:79], v[64:67], v[108:111], 0
	s_waitcnt lgkmcnt(0)
	v_mfma_f32_32x32x16_bf16 v[64:79], v[174:177], v[104:107], v[64:79]
	ds_read_b128 v[174:177], v170 offset:8768
	ds_read_b128 v[194:197], v170 offset:8800
	s_waitcnt lgkmcnt(1)
	v_mfma_f32_32x32x16_bf16 v[64:79], v[174:177], v[100:103], v[64:79]
	s_waitcnt lgkmcnt(0)
	v_mfma_f32_32x32x16_bf16 v[64:79], v[194:197], v[96:99], v[64:79]
	ds_read_b128 v[174:177], v170 offset:8832
	ds_read_b128 v[194:197], v170 offset:8864
	s_waitcnt lgkmcnt(1)
	v_mfma_f32_32x32x16_bf16 v[64:79], v[174:177], v[92:95], v[64:79]
	s_waitcnt lgkmcnt(0)
	v_mfma_f32_32x32x16_bf16 v[64:79], v[194:197], v[88:91], v[64:79]
	ds_read_b128 v[174:177], v170 offset:8896
	ds_read_b128 v[194:197], v170 offset:8928
	s_waitcnt lgkmcnt(1)
	v_mfma_f32_32x32x16_bf16 v[64:79], v[174:177], v[84:87], v[64:79]
	v_add_f32_e64 v174, v202, 0
	v_add_f32_e64 v175, v203, 0
	v_add_f32_e64 v174, v204, v174
	v_add_f32_e64 v175, v205, v175
	v_add_f32_e64 v174, v206, v174
	v_add_f32_e64 v175, v207, v175
	v_add_f32_e32 v174, v208, v174
	v_add_f32_e32 v175, v209, v175
	s_waitcnt lgkmcnt(0)
	v_mfma_f32_32x32x16_bf16 v[64:79], v[194:197], v[80:83], v[64:79]
	v_add_f32_e64 v174, v210, v174
	v_add_f32_e64 v175, v211, v175
	v_add_f32_e64 v174, v212, v174
	v_add_f32_e64 v175, v213, v175
	v_add_f32_e64 v174, v214, v174
	v_add_f32_e64 v175, v215, v175
	s_nop 5
	v_max_f32_e32 v152, v65, v65
	v_max_f32_e32 v173, v64, v64
	v_max_f32_e32 v152, v173, v152
	v_max3_f32 v152, v152, v66, v67
	v_max3_f32 v152, v152, v68, v69
	v_max3_f32 v152, v152, v70, v71
	v_max3_f32 v152, v152, v72, v73
	v_max3_f32 v152, v152, v74, v75
	v_max3_f32 v152, v152, v76, v77
	v_max3_f32 v152, v152, v78, v79
	ds_bpermute_b32 v173, v168, v152
	v_mfma_f32_32x32x16_bf16 v[32:47], v[178:181], v[182:185], v[32:47]
	v_add_f32_e64 v174, v216, v174
	v_add_f32_e64 v175, v217, v175
	s_waitcnt lgkmcnt(0)
	v_max_f32_e32 v173, v173, v173
	v_max_f32_e32 v152, v152, v173
	v_add_f32_e32 v174, v174, v175
	v_mul_f32_e32 v152, 0x3e0293ee, v152
	v_mfma_f32_32x32x16_bf16 v[16:31], v[186:189], v[182:185], v[16:31]
	v_add_f32_e32 v172, v172, v174
	v_cmp_gt_f32_e32 vcc, v152, v153
	v_mfma_f32_32x32x16_bf16 v[0:15], v[190:193], v[182:185], v[0:15]
	s_cbranch_vccnz .LBB0_1295
	v_mov_b32_e32 v152, v153
	s_branch .LBB0_1296
.LBB0_1301:
	s_barrier
	s_waitcnt vmcnt(3)
	ds_write_b128 v166, v[112:115]
	s_waitcnt vmcnt(2)
	ds_write_b128 v166, v[116:119] offset:4352
	s_waitcnt vmcnt(1)
	ds_write_b128 v166, v[120:123] offset:8704
	s_waitcnt vmcnt(0)
	ds_write_b128 v166, v[124:127] offset:13056
	ds_write_b128 v167, v[140:143] offset:17408
	ds_write_b128 v167, v[132:135] offset:22016
	ds_write_b128 v167, v[128:131] offset:26624
	ds_write_b128 v167, v[136:139] offset:31232
	s_waitcnt lgkmcnt(0)
	s_barrier
	ds_read_b128 v[64:67], v170
	ds_read_b128 v[112:115], v170 offset:32
	s_waitcnt lgkmcnt(1)
	v_mfma_f32_32x32x16_bf16 v[64:79], v[64:67], v[108:111], 0
	s_waitcnt lgkmcnt(0)
	v_mfma_f32_32x32x16_bf16 v[64:79], v[112:115], v[104:107], v[64:79]
	ds_read_b128 v[112:115], v170 offset:64
	ds_read_b128 v[116:119], v170 offset:96
	s_waitcnt lgkmcnt(1)
	v_mfma_f32_32x32x16_bf16 v[64:79], v[112:115], v[100:103], v[64:79]
	s_waitcnt lgkmcnt(0)
	v_mfma_f32_32x32x16_bf16 v[64:79], v[116:119], v[96:99], v[64:79]
	ds_read_b128 v[112:115], v170 offset:128
	ds_read_b128 v[116:119], v170 offset:160
	s_waitcnt lgkmcnt(1)
	v_mfma_f32_32x32x16_bf16 v[64:79], v[112:115], v[92:95], v[64:79]
	s_waitcnt lgkmcnt(0)
	v_mfma_f32_32x32x16_bf16 v[64:79], v[116:119], v[88:91], v[64:79]
	ds_read_b128 v[112:115], v170 offset:192
	ds_read_b128 v[116:119], v170 offset:224
	s_waitcnt lgkmcnt(1)
	v_mfma_f32_32x32x16_bf16 v[64:79], v[112:115], v[84:87], v[64:79]
	s_waitcnt lgkmcnt(0)
	v_mfma_f32_32x32x16_bf16 v[64:79], v[116:119], v[80:83], v[64:79]
	s_nop 11
	v_max_f32_e32 v112, v65, v65
	v_max_f32_e32 v113, v64, v64
	v_max_f32_e32 v112, v113, v112
	v_max3_f32 v112, v112, v66, v67
	v_max3_f32 v112, v112, v68, v69
	v_max3_f32 v112, v112, v70, v71
	v_max3_f32 v112, v112, v72, v73
	v_max3_f32 v112, v112, v74, v75
	v_max3_f32 v112, v112, v76, v77
	v_max3_f32 v112, v112, v78, v79
	ds_bpermute_b32 v113, v168, v112
	s_waitcnt lgkmcnt(0)
	v_max_f32_e32 v113, v113, v113
	v_max_f32_e32 v112, v112, v113
	v_mul_f32_e32 v112, 0x3e0293ee, v112
	v_cmp_gt_f32_e32 vcc, v112, v153
	s_cbranch_vccz .LBB0_1303
	v_max_f32_e32 v112, v112, v112
	v_max_f32_e32 v113, v153, v153
	v_max_f32_e32 v152, v113, v112
	v_sub_f32_e32 v112, v153, v152
	v_exp_f32_e32 v112, v112
	v_mov_b32_e32 v153, v152
	v_mul_f32_e32 v62, v62, v112
	v_mul_f32_e32 v63, v63, v112
	v_mul_f32_e32 v60, v60, v112
	v_mul_f32_e32 v61, v61, v112
	v_mul_f32_e32 v58, v58, v112
	v_mul_f32_e32 v59, v59, v112
	v_mul_f32_e32 v56, v56, v112
	v_mul_f32_e32 v57, v57, v112
	v_mul_f32_e32 v54, v54, v112
	v_mul_f32_e32 v55, v55, v112
	v_mul_f32_e32 v52, v52, v112
	v_mul_f32_e32 v53, v53, v112
	v_mul_f32_e32 v50, v50, v112
	v_mul_f32_e32 v51, v51, v112
	v_mul_f32_e32 v48, v48, v112
	v_mul_f32_e32 v49, v49, v112
	v_mul_f32_e32 v46, v46, v112
	v_mul_f32_e32 v47, v47, v112
	v_mul_f32_e32 v44, v44, v112
	v_mul_f32_e32 v45, v45, v112
	v_mul_f32_e32 v42, v42, v112
	v_mul_f32_e32 v43, v43, v112
	v_mul_f32_e32 v40, v40, v112
	v_mul_f32_e32 v41, v41, v112
	v_mul_f32_e32 v38, v38, v112
	v_mul_f32_e32 v39, v39, v112
	v_mul_f32_e32 v36, v36, v112
	v_mul_f32_e32 v37, v37, v112
	v_mul_f32_e32 v34, v34, v112
	v_mul_f32_e32 v35, v35, v112
	v_mul_f32_e32 v32, v32, v112
	v_mul_f32_e32 v33, v33, v112
	v_mul_f32_e32 v30, v30, v112
	v_mul_f32_e32 v31, v31, v112
	v_mul_f32_e32 v28, v28, v112
	v_mul_f32_e32 v29, v29, v112
	v_mul_f32_e32 v26, v26, v112
	v_mul_f32_e32 v27, v27, v112
	v_mul_f32_e32 v24, v24, v112
	v_mul_f32_e32 v25, v25, v112
	v_mul_f32_e32 v22, v22, v112
	v_mul_f32_e32 v23, v23, v112
	v_mul_f32_e32 v20, v20, v112
	v_mul_f32_e32 v21, v21, v112
	v_mul_f32_e32 v18, v18, v112
	v_mul_f32_e32 v19, v19, v112
	v_mul_f32_e32 v16, v16, v112
	v_mul_f32_e32 v17, v17, v112
	v_mul_f32_e32 v14, v14, v112
	v_mul_f32_e32 v15, v15, v112
	v_mul_f32_e32 v12, v12, v112
	v_mul_f32_e32 v13, v13, v112
	v_mul_f32_e32 v10, v10, v112
	v_mul_f32_e32 v11, v11, v112
	v_mul_f32_e32 v8, v8, v112
	v_mul_f32_e32 v9, v9, v112
	v_mul_f32_e32 v6, v6, v112
	v_mul_f32_e32 v7, v7, v112
	v_mul_f32_e32 v4, v4, v112
	v_mul_f32_e32 v5, v5, v112
	v_mul_f32_e32 v2, v2, v112
	v_mul_f32_e32 v3, v3, v112
	v_mul_f32_e32 v0, v0, v112
	v_mul_f32_e32 v1, v1, v112
	v_mul_f32_e32 v172, v172, v112
	v_mov_b32_e32 v112, v152
	s_branch .LBB0_1304

.LBB0_1304:
	v_fma_f32 v64, v64, s18, -v152
	v_fma_f32 v65, v65, s18, -v153
	v_fma_f32 v72, v72, s18, -v152
	v_fma_f32 v73, v73, s18, -v153
	v_exp_f32_e32 v134, v64
	v_exp_f32_e32 v135, v65
	v_fma_f32 v64, v66, s18, -v152
	v_fma_f32 v65, v67, s18, -v153
	ds_read_b128 v[114:117], v171 offset:17440
	v_exp_f32_e32 v136, v64
	v_exp_f32_e32 v137, v65
	v_fma_f32 v64, v68, s18, -v152
	v_fma_f32 v65, v69, s18, -v153
	v_fma_f32 v68, v70, s18, -v152
	v_fma_f32 v69, v71, s18, -v153
	v_exp_f32_e32 v138, v64
	v_exp_f32_e32 v139, v65
	ds_read_b128 v[64:67], v171 offset:17408
	v_exp_f32_e32 v140, v68
	v_exp_f32_e32 v141, v69
	v_cvt_pk_bf16_f32 v68, v134, v135
	v_cvt_pk_bf16_f32 v69, v136, v137
	v_cvt_pk_bf16_f32 v70, v138, v139
	v_cvt_pk_bf16_f32 v71, v140, v141
	v_exp_f32_e32 v142, v72
	v_exp_f32_e32 v143, v73
	s_waitcnt lgkmcnt(0)
	v_mfma_f32_32x32x16_bf16 v[48:63], v[64:67], v[68:71], v[48:63]
	ds_read_b128 v[64:67], v171 offset:22016
	ds_read_b128 v[118:121], v171 offset:22048
	s_waitcnt lgkmcnt(1)
	v_mfma_f32_32x32x16_bf16 v[32:47], v[64:67], v[68:71], v[32:47]
	ds_read_b128 v[64:67], v171 offset:26624
	ds_read_b128 v[122:125], v171 offset:31232
	ds_read_b128 v[126:129], v171 offset:26656
	ds_read_b128 v[130:133], v171 offset:31264
	s_waitcnt lgkmcnt(3)
	v_mfma_f32_32x32x16_bf16 v[16:31], v[64:67], v[68:71], v[16:31]
	v_fma_f32 v64, v74, s18, -v152
	v_fma_f32 v65, v75, s18, -v153
	v_exp_f32_e32 v154, v64
	v_exp_f32_e32 v155, v65
	v_fma_f32 v64, v76, s18, -v152
	v_fma_f32 v65, v77, s18, -v153
	s_nop 0
	v_exp_f32_e32 v156, v64
	v_exp_f32_e32 v157, v65
	v_fma_f32 v64, v78, s18, -v152
	v_fma_f32 v65, v79, s18, -v153
	s_waitcnt lgkmcnt(2)
	v_mfma_f32_32x32x16_bf16 v[0:15], v[122:125], v[68:71], v[0:15]
	v_exp_f32_e32 v158, v64
	v_exp_f32_e32 v159, v65
	v_cvt_pk_bf16_f32 v122, v142, v143
	v_cvt_pk_bf16_f32 v123, v154, v155
	v_cvt_pk_bf16_f32 v124, v156, v157
	v_cvt_pk_bf16_f32 v125, v158, v159
	s_nop 1
	v_mfma_f32_32x32x16_bf16 v[48:63], v[114:117], v[122:125], v[48:63]
	ds_read_b128 v[64:67], v170 offset:8704
	ds_read_b128 v[114:117], v170 offset:8736
	s_waitcnt lgkmcnt(1)
	v_mfma_f32_32x32x16_bf16 v[64:79], v[64:67], v[108:111], 0
	s_waitcnt lgkmcnt(0)
	v_mfma_f32_32x32x16_bf16 v[64:79], v[114:117], v[104:107], v[64:79]
	ds_read_b128 v[104:107], v170 offset:8768
	ds_read_b128 v[108:111], v170 offset:8800
	s_waitcnt lgkmcnt(1)
	v_mfma_f32_32x32x16_bf16 v[64:79], v[104:107], v[100:103], v[64:79]
	s_waitcnt lgkmcnt(0)
	v_mfma_f32_32x32x16_bf16 v[64:79], v[108:111], v[96:99], v[64:79]
	ds_read_b128 v[96:99], v170 offset:8832
	ds_read_b128 v[100:103], v170 offset:8864
	s_waitcnt lgkmcnt(1)
	v_mfma_f32_32x32x16_bf16 v[64:79], v[96:99], v[92:95], v[64:79]
	s_waitcnt lgkmcnt(0)
	v_mfma_f32_32x32x16_bf16 v[64:79], v[100:103], v[88:91], v[64:79]
	ds_read_b128 v[88:91], v170 offset:8896
	ds_read_b128 v[92:95], v170 offset:8928
	s_waitcnt lgkmcnt(1)
	v_mfma_f32_32x32x16_bf16 v[64:79], v[88:91], v[84:87], v[64:79]
	v_add_f32_e64 v84, v134, 0
	v_add_f32_e64 v85, v135, 0
	v_add_f32_e64 v84, v136, v84
	v_add_f32_e64 v85, v137, v85
	v_add_f32_e64 v84, v138, v84
	v_add_f32_e64 v85, v139, v85
	v_add_f32_e32 v84, v140, v84
	v_add_f32_e32 v85, v141, v85
	s_waitcnt lgkmcnt(0)
	v_mfma_f32_32x32x16_bf16 v[64:79], v[92:95], v[80:83], v[64:79]
	v_add_f32_e64 v80, v142, v84
	v_add_f32_e64 v81, v143, v85
	v_add_f32_e64 v80, v154, v80
	v_add_f32_e64 v81, v155, v81
	v_add_f32_e64 v80, v156, v80
	v_add_f32_e64 v81, v157, v81
	s_nop 5
	v_max_f32_e32 v82, v65, v65
	v_max_f32_e32 v83, v64, v64
	v_max_f32_e32 v82, v83, v82
	v_max3_f32 v82, v82, v66, v67
	v_max3_f32 v82, v82, v68, v69
	v_max3_f32 v82, v82, v70, v71
	v_max3_f32 v82, v82, v72, v73
	v_max3_f32 v82, v82, v74, v75
	v_max3_f32 v82, v82, v76, v77
	v_max3_f32 v82, v82, v78, v79
	ds_bpermute_b32 v83, v168, v82
	v_mfma_f32_32x32x16_bf16 v[32:47], v[118:121], v[122:125], v[32:47]
	v_add_f32_e64 v80, v158, v80
	v_add_f32_e64 v81, v159, v81
	v_add_f32_e32 v80, v80, v81
	s_waitcnt lgkmcnt(0)
	v_max_f32_e32 v81, v83, v83
	v_max_f32_e32 v81, v82, v81
	v_mul_f32_e32 v81, 0x3e0293ee, v81
	v_add_f32_e32 v80, v172, v80
	v_mfma_f32_32x32x16_bf16 v[16:31], v[126:129], v[122:125], v[16:31]
	v_cmp_gt_f32_e32 vcc, v81, v112
	v_mfma_f32_32x32x16_bf16 v[0:15], v[130:133], v[122:125], v[0:15]
	s_cbranch_vccz .LBB0_1285
	v_max_f32_e32 v81, v81, v81
	v_max_f32_e32 v82, v112, v112
	v_max_f32_e32 v152, v82, v81
	v_sub_f32_e32 v81, v112, v152
	v_exp_f32_e32 v82, v81
	v_mov_b32_e32 v153, v152
	v_mul_f32_e32 v62, v62, v82
	v_mul_f32_e32 v63, v63, v82
	v_mul_f32_e32 v60, v60, v82
	v_mul_f32_e32 v61, v61, v82
	v_mul_f32_e32 v58, v58, v82
	v_mul_f32_e32 v59, v59, v82
	v_mul_f32_e32 v56, v56, v82
	v_mul_f32_e32 v57, v57, v82
	v_mul_f32_e32 v54, v54, v82
	v_mul_f32_e32 v55, v55, v82
	v_mul_f32_e32 v52, v52, v82
	v_mul_f32_e32 v53, v53, v82
	v_mul_f32_e32 v50, v50, v82
	v_mul_f32_e32 v51, v51, v82
	v_mul_f32_e32 v48, v48, v82
	v_mul_f32_e32 v49, v49, v82
	v_mul_f32_e32 v46, v46, v82
	v_mul_f32_e32 v47, v47, v82
	v_mul_f32_e32 v44, v44, v82
	v_mul_f32_e32 v45, v45, v82
	v_mul_f32_e32 v42, v42, v82
	v_mul_f32_e32 v43, v43, v82
	v_mul_f32_e32 v40, v40, v82
	v_mul_f32_e32 v41, v41, v82
	v_mul_f32_e32 v38, v38, v82
	v_mul_f32_e32 v39, v39, v82
	v_mul_f32_e32 v36, v36, v82
	v_mul_f32_e32 v37, v37, v82
	v_mul_f32_e32 v34, v34, v82
	v_mul_f32_e32 v35, v35, v82
	v_mul_f32_e32 v32, v32, v82
	v_mul_f32_e32 v33, v33, v82
	v_mul_f32_e32 v30, v30, v82
	v_mul_f32_e32 v31, v31, v82
	v_mul_f32_e32 v28, v28, v82
	v_mul_f32_e32 v29, v29, v82
	v_mul_f32_e32 v26, v26, v82
	v_mul_f32_e32 v27, v27, v82
	v_mul_f32_e32 v24, v24, v82
	v_mul_f32_e32 v25, v25, v82
	v_mul_f32_e32 v22, v22, v82
	v_mul_f32_e32 v23, v23, v82
	v_mul_f32_e32 v20, v20, v82
	v_mul_f32_e32 v21, v21, v82
	v_mul_f32_e32 v18, v18, v82
	v_mul_f32_e32 v19, v19, v82
	v_mul_f32_e32 v16, v16, v82
	v_mul_f32_e32 v17, v17, v82
	v_mul_f32_e32 v14, v14, v82
	v_mul_f32_e32 v15, v15, v82
	v_mul_f32_e32 v12, v12, v82
	v_mul_f32_e32 v13, v13, v82
	v_mul_f32_e32 v10, v10, v82
	v_mul_f32_e32 v11, v11, v82
	v_mul_f32_e32 v8, v8, v82
	v_mul_f32_e32 v9, v9, v82
	v_mul_f32_e32 v6, v6, v82
	v_mul_f32_e32 v7, v7, v82
	v_mul_f32_e32 v4, v4, v82
	v_mul_f32_e32 v5, v5, v82
	v_mul_f32_e32 v2, v2, v82
	v_mul_f32_e32 v3, v3, v82
	v_mul_f32_e32 v0, v0, v82
	v_mul_f32_e32 v1, v1, v82
	v_mul_f32_e32 v80, v80, v82
	s_branch .LBB0_1285
